# stream GEMM K loops: second LDS-DMA of each stage derives m0 with s_bitset1_b32 m0,13 instead of a second v_readfirstlane+s_mov (instruction selection on the load side)
# baseline (speedup 1.0000x reference)
.LBB0_32:
	s_add_i32 s11, s10, 2
	ds_read_b128 v[132:135], v159
	ds_read_b128 v[136:139], v160
	ds_read_b128 v[180:183], v161
	ds_read_b128 v[184:187], v162
	s_cmpk_lt_u32 s10, 0x56
	s_cselect_b32 s12, s8, s5
	s_cselect_b32 s13, s7, s6
	s_cselect_b32 s14, s9, 0
	s_mulk_i32 s13, 0x1600
	s_mulk_i32 s12, 0x1600
	s_or_b32 s15, s14, 64
	s_add_i32 s17, s12, s14
	s_add_i32 s18, s13, 0xb0000
	s_add_i32 s16, s13, s14
	s_add_i32 s13, s15, s13
	s_add_i32 s12, s15, s12
	s_lshl_b32 s17, s17, 1
	s_add_i32 s14, s18, s14
	s_add_i32 s18, s18, s15
	s_addk_i32 s9, 0x80
	s_lshl_b32 s16, s16, 1
	s_lshl_b32 s19, s13, 1
	s_lshl_b32 s13, s12, 1
	s_lshl_b32 s14, s14, 1
	s_add_i32 s15, s17, 0x160000
	s_lshl_b32 s12, s18, 1
	s_cmpk_gt_u32 s10, 0x55
	v_readfirstlane_b32 s10, v163
	v_add_u32_e32 v131, 0xfff50000, v130
	s_mov_b32 m0, s10
	ds_read_b128 v[188:191], v157
	ds_read_b128 v[192:195], v157 offset:1024
	ds_read_b128 v[196:199], v157 offset:2048
	ds_read_b128 v[200:203], v157 offset:3072
	ds_read_b128 v[204:207], v157 offset:4096
	ds_read_b128 v[208:211], v157 offset:5120
	ds_read_b128 v[212:215], v157 offset:6144
	ds_read_b128 v[216:219], v157 offset:7168
	global_load_lds_dwordx4 v131, s[76:77]
	s_bitset1_b32 m0, 13
	s_nop 0
	global_load_lds_dwordx4 v130, s[76:77]
	s_waitcnt lgkmcnt(8)
	ds_read_b128 v[220:223], v166
	ds_read_b128 v[242:245], v167
	ds_read_b128 v[246:249], v168
	ds_read_b128 v[250:253], v169
	s_waitcnt vmcnt(8)
	s_waitcnt lgkmcnt(0)
	s_barrier
	s_setprio 1
	v_mfma_f32_16x16x32_bf16 v[126:129], v[132:135], v[188:191], v[126:129]
	v_mfma_f32_16x16x32_bf16 v[122:125], v[180:183], v[188:191], v[122:125]
	v_mfma_f32_16x16x32_bf16 v[118:121], v[132:135], v[196:199], v[118:121]
	v_mfma_f32_16x16x32_bf16 v[114:117], v[180:183], v[196:199], v[114:117]
	v_mfma_f32_16x16x32_bf16 v[110:113], v[132:135], v[204:207], v[110:113]
	v_mfma_f32_16x16x32_bf16 v[106:109], v[180:183], v[204:207], v[106:109]
	v_mfma_f32_16x16x32_bf16 v[102:105], v[132:135], v[212:215], v[102:105]
	v_mfma_f32_16x16x32_bf16 v[98:101], v[180:183], v[212:215], v[98:101]
	v_mfma_f32_16x16x32_bf16 v[126:129], v[136:139], v[192:195], v[126:129]
	v_mfma_f32_16x16x32_bf16 v[122:125], v[184:187], v[192:195], v[122:125]
	v_mfma_f32_16x16x32_bf16 v[118:121], v[136:139], v[200:203], v[118:121]
	v_mfma_f32_16x16x32_bf16 v[114:117], v[184:187], v[200:203], v[114:117]
	v_mfma_f32_16x16x32_bf16 v[110:113], v[136:139], v[208:211], v[110:113]
	v_mfma_f32_16x16x32_bf16 v[106:109], v[184:187], v[208:211], v[106:109]
	v_mfma_f32_16x16x32_bf16 v[102:105], v[136:139], v[216:219], v[102:105]
	v_mfma_f32_16x16x32_bf16 v[98:101], v[184:187], v[216:219], v[98:101]
	v_mfma_f32_16x16x32_bf16 v[94:97], v[220:223], v[188:191], v[94:97]
	v_mfma_f32_16x16x32_bf16 v[90:93], v[246:249], v[188:191], v[90:93]
	v_mfma_f32_16x16x32_bf16 v[86:89], v[220:223], v[196:199], v[86:89]
	v_mfma_f32_16x16x32_bf16 v[82:85], v[246:249], v[196:199], v[82:85]
	v_mfma_f32_16x16x32_bf16 v[78:81], v[220:223], v[204:207], v[78:81]
	v_mfma_f32_16x16x32_bf16 v[74:77], v[246:249], v[204:207], v[74:77]
	v_mfma_f32_16x16x32_bf16 v[70:73], v[220:223], v[212:215], v[70:73]
	v_mfma_f32_16x16x32_bf16 v[66:69], v[246:249], v[212:215], v[66:69]
	v_mfma_f32_16x16x32_bf16 v[94:97], v[242:245], v[192:195], v[94:97]
	v_mfma_f32_16x16x32_bf16 v[90:93], v[250:253], v[192:195], v[90:93]
	v_mfma_f32_16x16x32_bf16 v[86:89], v[242:245], v[200:203], v[86:89]
	v_mfma_f32_16x16x32_bf16 v[82:85], v[250:253], v[200:203], v[82:85]
	v_mfma_f32_16x16x32_bf16 v[78:81], v[242:245], v[208:211], v[78:81]
	v_mfma_f32_16x16x32_bf16 v[74:77], v[250:253], v[208:211], v[74:77]
	v_mfma_f32_16x16x32_bf16 v[70:73], v[242:245], v[216:219], v[70:73]
	v_mfma_f32_16x16x32_bf16 v[66:69], v[250:253], v[216:219], v[66:69]
	s_setprio 0
	s_barrier
	v_readfirstlane_b32 s10, v144
	v_add_u32_e32 v131, s16, v142
	s_mov_b32 m0, s10
	global_load_lds_dwordx4 v131, s[78:79]
	v_add_u32_e32 v131, s16, v143
	s_bitset1_b32 m0, 13
	s_nop 0
	global_load_lds_dwordx4 v131, s[78:79]
	v_readfirstlane_b32 s10, v0
	v_add_u32_e32 v131, s17, v142
	s_mov_b32 m0, s10
	ds_read_b128 v[188:191], v157 offset:16384
	ds_read_b128 v[192:195], v157 offset:17408
	ds_read_b128 v[196:199], v157 offset:18432
	ds_read_b128 v[200:203], v157 offset:19456
	ds_read_b128 v[204:207], v157 offset:20480
	ds_read_b128 v[208:211], v157 offset:21504
	ds_read_b128 v[212:215], v157 offset:22528
	ds_read_b128 v[216:219], v157 offset:23552
	global_load_lds_dwordx4 v131, s[76:77]
	v_add_u32_e32 v131, s17, v143
	s_bitset1_b32 m0, 13
	s_nop 0
	global_load_lds_dwordx4 v131, s[76:77]
	v_readfirstlane_b32 s10, v147
	v_add_u32_e32 v131, s14, v142
	s_mov_b32 m0, s10
	global_load_lds_dwordx4 v131, s[78:79]
	v_add_u32_e32 v131, s14, v143
	s_bitset1_b32 m0, 13
	s_nop 0
	global_load_lds_dwordx4 v131, s[78:79]
	s_waitcnt vmcnt(8)
	s_waitcnt lgkmcnt(0)
	s_barrier
	s_setprio 1
	v_mfma_f32_16x16x32_bf16 v[62:65], v[132:135], v[188:191], v[62:65]
	v_mfma_f32_16x16x32_bf16 v[58:61], v[180:183], v[188:191], v[58:61]
	v_mfma_f32_16x16x32_bf16 v[54:57], v[132:135], v[196:199], v[54:57]
	v_mfma_f32_16x16x32_bf16 v[50:53], v[180:183], v[196:199], v[50:53]
	v_mfma_f32_16x16x32_bf16 v[46:49], v[132:135], v[204:207], v[46:49]
	v_mfma_f32_16x16x32_bf16 v[42:45], v[180:183], v[204:207], v[42:45]
	v_mfma_f32_16x16x32_bf16 v[38:41], v[132:135], v[212:215], v[38:41]
	v_mfma_f32_16x16x32_bf16 v[34:37], v[180:183], v[212:215], v[34:37]
	v_mfma_f32_16x16x32_bf16 v[62:65], v[136:139], v[192:195], v[62:65]
	v_mfma_f32_16x16x32_bf16 v[58:61], v[184:187], v[192:195], v[58:61]
	v_mfma_f32_16x16x32_bf16 v[54:57], v[136:139], v[200:203], v[54:57]
	v_mfma_f32_16x16x32_bf16 v[50:53], v[184:187], v[200:203], v[50:53]
	v_mfma_f32_16x16x32_bf16 v[46:49], v[136:139], v[208:211], v[46:49]
	v_mfma_f32_16x16x32_bf16 v[42:45], v[184:187], v[208:211], v[42:45]
	v_mfma_f32_16x16x32_bf16 v[38:41], v[136:139], v[216:219], v[38:41]
	v_mfma_f32_16x16x32_bf16 v[34:37], v[184:187], v[216:219], v[34:37]
	v_mfma_f32_16x16x32_bf16 v[30:33], v[220:223], v[188:191], v[30:33]
	v_mfma_f32_16x16x32_bf16 v[26:29], v[246:249], v[188:191], v[26:29]
	v_mfma_f32_16x16x32_bf16 v[22:25], v[220:223], v[196:199], v[22:25]
	v_mfma_f32_16x16x32_bf16 v[18:21], v[246:249], v[196:199], v[18:21]
	v_mfma_f32_16x16x32_bf16 v[14:17], v[220:223], v[204:207], v[14:17]
	v_mfma_f32_16x16x32_bf16 v[10:13], v[246:249], v[204:207], v[10:13]
	v_mfma_f32_16x16x32_bf16 v[6:9], v[220:223], v[212:215], v[6:9]
	v_mfma_f32_16x16x32_bf16 v[2:5], v[246:249], v[212:215], v[2:5]
	v_mfma_f32_16x16x32_bf16 v[30:33], v[242:245], v[192:195], v[30:33]
	v_mfma_f32_16x16x32_bf16 v[26:29], v[250:253], v[192:195], v[26:29]
	v_mfma_f32_16x16x32_bf16 v[22:25], v[242:245], v[200:203], v[22:25]
	v_mfma_f32_16x16x32_bf16 v[18:21], v[250:253], v[200:203], v[18:21]
	v_mfma_f32_16x16x32_bf16 v[14:17], v[242:245], v[208:211], v[14:17]
	v_mfma_f32_16x16x32_bf16 v[10:13], v[250:253], v[208:211], v[10:13]
	v_mfma_f32_16x16x32_bf16 v[6:9], v[242:245], v[216:219], v[6:9]
	v_mfma_f32_16x16x32_bf16 v[2:5], v[250:253], v[216:219], v[2:5]
	s_setprio 0
	s_barrier
	ds_read_b128 v[132:135], v170
	ds_read_b128 v[136:139], v171
	ds_read_b128 v[180:183], v172
	ds_read_b128 v[184:187], v173
	v_readfirstlane_b32 s10, v149
	v_add_u32_e32 v131, s15, v142
	s_mov_b32 m0, s10
	ds_read_b128 v[188:191], v157 offset:32768
	ds_read_b128 v[192:195], v157 offset:33792
	ds_read_b128 v[196:199], v157 offset:34816
	ds_read_b128 v[200:203], v157 offset:35840
	ds_read_b128 v[204:207], v157 offset:36864
	ds_read_b128 v[208:211], v157 offset:37888
	ds_read_b128 v[212:215], v157 offset:38912
	ds_read_b128 v[216:219], v157 offset:39936
	global_load_lds_dwordx4 v131, s[76:77]
	v_add_u32_e32 v131, s15, v143
	s_bitset1_b32 m0, 13
	s_nop 0
	global_load_lds_dwordx4 v131, s[76:77]
	s_waitcnt lgkmcnt(8)
	ds_read_b128 v[220:223], v174
	ds_read_b128 v[242:245], v175
	ds_read_b128 v[246:249], v176
	ds_read_b128 v[250:253], v177
	s_waitcnt vmcnt(8)
	s_waitcnt lgkmcnt(0)
	s_barrier
	s_setprio 1
	v_mfma_f32_16x16x32_bf16 v[126:129], v[132:135], v[188:191], v[126:129]
	v_mfma_f32_16x16x32_bf16 v[122:125], v[180:183], v[188:191], v[122:125]
	v_mfma_f32_16x16x32_bf16 v[118:121], v[132:135], v[196:199], v[118:121]
	v_mfma_f32_16x16x32_bf16 v[114:117], v[180:183], v[196:199], v[114:117]
	v_mfma_f32_16x16x32_bf16 v[110:113], v[132:135], v[204:207], v[110:113]
	v_mfma_f32_16x16x32_bf16 v[106:109], v[180:183], v[204:207], v[106:109]
	v_mfma_f32_16x16x32_bf16 v[102:105], v[132:135], v[212:215], v[102:105]
	v_mfma_f32_16x16x32_bf16 v[98:101], v[180:183], v[212:215], v[98:101]
	v_mfma_f32_16x16x32_bf16 v[126:129], v[136:139], v[192:195], v[126:129]
	v_mfma_f32_16x16x32_bf16 v[122:125], v[184:187], v[192:195], v[122:125]
	v_mfma_f32_16x16x32_bf16 v[118:121], v[136:139], v[200:203], v[118:121]
	v_mfma_f32_16x16x32_bf16 v[114:117], v[184:187], v[200:203], v[114:117]
	v_mfma_f32_16x16x32_bf16 v[110:113], v[136:139], v[208:211], v[110:113]
	v_mfma_f32_16x16x32_bf16 v[106:109], v[184:187], v[208:211], v[106:109]
	v_mfma_f32_16x16x32_bf16 v[102:105], v[136:139], v[216:219], v[102:105]
	v_mfma_f32_16x16x32_bf16 v[98:101], v[184:187], v[216:219], v[98:101]
	v_mfma_f32_16x16x32_bf16 v[94:97], v[220:223], v[188:191], v[94:97]
	v_mfma_f32_16x16x32_bf16 v[90:93], v[246:249], v[188:191], v[90:93]
	v_mfma_f32_16x16x32_bf16 v[86:89], v[220:223], v[196:199], v[86:89]
	v_mfma_f32_16x16x32_bf16 v[82:85], v[246:249], v[196:199], v[82:85]
	v_mfma_f32_16x16x32_bf16 v[78:81], v[220:223], v[204:207], v[78:81]
	v_mfma_f32_16x16x32_bf16 v[74:77], v[246:249], v[204:207], v[74:77]
	v_mfma_f32_16x16x32_bf16 v[70:73], v[220:223], v[212:215], v[70:73]
	v_mfma_f32_16x16x32_bf16 v[66:69], v[246:249], v[212:215], v[66:69]
	v_mfma_f32_16x16x32_bf16 v[94:97], v[242:245], v[192:195], v[94:97]
	v_mfma_f32_16x16x32_bf16 v[90:93], v[250:253], v[192:195], v[90:93]
	v_mfma_f32_16x16x32_bf16 v[86:89], v[242:245], v[200:203], v[86:89]
	v_mfma_f32_16x16x32_bf16 v[82:85], v[250:253], v[200:203], v[82:85]
	v_mfma_f32_16x16x32_bf16 v[78:81], v[242:245], v[208:211], v[78:81]
	v_mfma_f32_16x16x32_bf16 v[74:77], v[250:253], v[208:211], v[74:77]
	v_mfma_f32_16x16x32_bf16 v[70:73], v[242:245], v[216:219], v[70:73]
	v_mfma_f32_16x16x32_bf16 v[66:69], v[250:253], v[216:219], v[66:69]
	s_setprio 0
	s_barrier
; DI void gemm_resid(const u16* A, const u16* Bt, int K, const float* xin, float* xout, int bid, int nb, int tid) {
;     ...
; #pragma unroll
;     for (int ai = 0; ai < 2; ++ai)
; #pragma unroll
;       for (int bj = 0; bj < 2; ++bj) {
;         float4 xi[4][2];
; #pragma unroll
;         for (int m = 0; m < 4; ++m)
; #pragma unroll
;           for (int n = 0; n < 2; ++n) xi[m][n] = *reinterpret_cast<const float4*>(xin + (size_t)ACC_ROW * 2048 + ACC_COL);
	v_readfirstlane_b32 s10, v151
	v_add_u32_e32 v131, s19, v142
	s_mov_b32 m0, s10
	global_load_lds_dwordx4 v131, s[78:79]
	v_add_u32_e32 v131, s19, v143
	s_bitset1_b32 m0, 13
	s_nop 0
	global_load_lds_dwordx4 v131, s[78:79]
	v_readfirstlane_b32 s10, v153
	v_add_u32_e32 v131, s13, v142
	s_mov_b32 m0, s10
	ds_read_b128 v[188:191], v157 offset:49152
	ds_read_b128 v[192:195], v157 offset:50176
	ds_read_b128 v[196:199], v157 offset:51200
	ds_read_b128 v[200:203], v157 offset:52224
	ds_read_b128 v[204:207], v157 offset:53248
	ds_read_b128 v[208:211], v157 offset:54272
	ds_read_b128 v[212:215], v157 offset:55296
	ds_read_b128 v[216:219], v157 offset:56320
	global_load_lds_dwordx4 v131, s[76:77]
	v_add_u32_e32 v131, s13, v143
	s_bitset1_b32 m0, 13
	s_nop 0
	global_load_lds_dwordx4 v131, s[76:77]
	v_readfirstlane_b32 s10, v155
	v_add_u32_e32 v131, s12, v142
	s_mov_b32 m0, s10
	global_load_lds_dwordx4 v131, s[78:79]
	v_add_u32_e32 v131, s12, v143
	s_bitset1_b32 m0, 13
	s_nop 0
	global_load_lds_dwordx4 v131, s[78:79]
	s_waitcnt vmcnt(8)
	s_waitcnt lgkmcnt(0)
	s_barrier
	s_setprio 1
	v_mfma_f32_16x16x32_bf16 v[62:65], v[132:135], v[188:191], v[62:65]
	v_mfma_f32_16x16x32_bf16 v[58:61], v[180:183], v[188:191], v[58:61]
	v_mfma_f32_16x16x32_bf16 v[54:57], v[132:135], v[196:199], v[54:57]
	v_mfma_f32_16x16x32_bf16 v[50:53], v[180:183], v[196:199], v[50:53]
	v_mfma_f32_16x16x32_bf16 v[46:49], v[132:135], v[204:207], v[46:49]
	v_mfma_f32_16x16x32_bf16 v[42:45], v[180:183], v[204:207], v[42:45]
	v_mfma_f32_16x16x32_bf16 v[38:41], v[132:135], v[212:215], v[38:41]
	v_mfma_f32_16x16x32_bf16 v[34:37], v[180:183], v[212:215], v[34:37]
	v_mfma_f32_16x16x32_bf16 v[62:65], v[136:139], v[192:195], v[62:65]
	v_mfma_f32_16x16x32_bf16 v[58:61], v[184:187], v[192:195], v[58:61]
	v_mfma_f32_16x16x32_bf16 v[54:57], v[136:139], v[200:203], v[54:57]
	v_mfma_f32_16x16x32_bf16 v[50:53], v[184:187], v[200:203], v[50:53]
	v_mfma_f32_16x16x32_bf16 v[46:49], v[136:139], v[208:211], v[46:49]
	v_mfma_f32_16x16x32_bf16 v[42:45], v[184:187], v[208:211], v[42:45]
	v_mfma_f32_16x16x32_bf16 v[38:41], v[136:139], v[216:219], v[38:41]
	v_mfma_f32_16x16x32_bf16 v[34:37], v[184:187], v[216:219], v[34:37]
	v_mfma_f32_16x16x32_bf16 v[30:33], v[220:223], v[188:191], v[30:33]
	v_mfma_f32_16x16x32_bf16 v[26:29], v[246:249], v[188:191], v[26:29]
	v_mfma_f32_16x16x32_bf16 v[22:25], v[220:223], v[196:199], v[22:25]
	v_mfma_f32_16x16x32_bf16 v[18:21], v[246:249], v[196:199], v[18:21]
	v_mfma_f32_16x16x32_bf16 v[14:17], v[220:223], v[204:207], v[14:17]
	v_mfma_f32_16x16x32_bf16 v[10:13], v[246:249], v[204:207], v[10:13]
	v_mfma_f32_16x16x32_bf16 v[6:9], v[220:223], v[212:215], v[6:9]
	v_mfma_f32_16x16x32_bf16 v[2:5], v[246:249], v[212:215], v[2:5]
	v_mfma_f32_16x16x32_bf16 v[30:33], v[242:245], v[192:195], v[30:33]
	v_mfma_f32_16x16x32_bf16 v[26:29], v[250:253], v[192:195], v[26:29]
	v_mfma_f32_16x16x32_bf16 v[22:25], v[242:245], v[200:203], v[22:25]
	v_mfma_f32_16x16x32_bf16 v[18:21], v[250:253], v[200:203], v[18:21]
	v_mfma_f32_16x16x32_bf16 v[14:17], v[242:245], v[208:211], v[14:17]
	v_mfma_f32_16x16x32_bf16 v[10:13], v[250:253], v[208:211], v[10:13]
	v_mfma_f32_16x16x32_bf16 v[6:9], v[242:245], v[216:219], v[6:9]
	v_mfma_f32_16x16x32_bf16 v[2:5], v[250:253], v[216:219], v[2:5]
	s_setprio 0
	v_add_u32_e32 v130, 0x100, v130
	s_mov_b32 s10, s11
	s_barrier
	s_cbranch_scc0 .LBB0_32
	v_mov_b32_e32 v131, v239
	s_nop 0
	v_ashrrev_i32_e32 v130, 2, v131
	v_and_b32_e32 v130, 0xffffffc0, v130
	v_and_or_b32 v132, v131, 15, s8
	v_add_u32_e32 v130, v132, v130
	v_lshrrev_b32_e32 v132, 1, v131
	v_lshrrev_b32_e32 v131, 2, v131
	v_and_b32_e32 v132, 0x60, v132
	v_and_b32_e32 v131, 12, v131
	v_or3_b32 v132, v132, v131, s7
	v_ashrrev_i32_e32 v131, 31, v130
	v_ashrrev_i32_e32 v133, 31, v132
	v_lshlrev_b64 v[134:135], 13, v[130:131]
	v_lshl_add_u64 v[134:135], s[72:73], 0, v[134:135]
	v_lshlrev_b64 v[132:133], 2, v[132:133]
	v_lshl_add_u64 v[140:141], v[134:135], 0, v[132:133]
	v_or_b32_e32 v134, 16, v130
	v_ashrrev_i32_e32 v135, 31, v134
	v_lshlrev_b64 v[134:135], 13, v[134:135]
	v_lshl_add_u64 v[134:135], s[72:73], 0, v[134:135]
	v_lshl_add_u64 v[138:139], v[134:135], 0, v[132:133]
	v_or_b32_e32 v134, 32, v130
	v_ashrrev_i32_e32 v135, 31, v134
	v_lshlrev_b64 v[134:135], 13, v[134:135]
	v_lshl_add_u64 v[134:135], s[72:73], 0, v[134:135]
	v_lshl_add_u64 v[136:137], v[134:135], 0, v[132:133]
	v_or_b32_e32 v134, 48, v130
	v_ashrrev_i32_e32 v135, 31, v134
	v_lshlrev_b64 v[134:135], 13, v[134:135]
	v_lshl_add_u64 v[134:135], s[72:73], 0, v[134:135]
	v_lshl_add_u64 v[134:135], v[134:135], 0, v[132:133]
	global_load_dwordx4 v[180:183], v[140:141], off
	global_load_dwordx4 v[184:187], v[140:141], off offset:64
	global_load_dwordx4 v[188:191], v[138:139], off
	global_load_dwordx4 v[192:195], v[138:139], off offset:64
	global_load_dwordx4 v[196:199], v[136:137], off
	global_load_dwordx4 v[200:203], v[136:137], off offset:64
	global_load_dwordx4 v[204:207], v[134:135], off
	global_load_dwordx4 v[208:211], v[134:135], off offset:64
	s_waitcnt vmcnt(0)
; #define EPI_SCHED __builtin_amdgcn_sched_barrier(0)
; DI void gemm_resid(const u16* A, const u16* Bt, int K, const float* xin, float* xout, int bid, int nb, int tid) {
;     ...
; #pragma unroll
;     for (int ai = 0; ai < 2; ++ai)
; #pragma unroll
;       for (int bj = 0; bj < 2; ++bj) {
;         float4 xi[4][2];
; #pragma unroll
;         for (int m = 0; m < 4; ++m)
; #pragma unroll
;           for (int n = 0; n < 2; ++n) xi[m][n] = *reinterpret_cast<const float4*>(xin + (size_t)ACC_ROW * 2048 + ACC_COL);
; #pragma unroll
;         for (int m = 0; m < 4; ++m)
; #pragma unroll
;           for (int n = 0; n < 2; ++n) {
;             const f32x4 v = acc[ai][bj][m][n];
;             float4 r; r.x = xi[m][n].x + v[0]; r.y = xi[m][n].y + v[1]; r.z = xi[m][n].z + v[2]; r.w = xi[m][n].w + v[3];
;             *reinterpret_cast<float4*>(xout + (size_t)ACC_ROW * 2048 + ACC_COL) = r;
;           }
;         EPI_SCHED;
;       }
	v_pk_add_f32 v[126:127], v[126:127], v[180:181]
	v_pk_add_f32 v[128:129], v[128:129], v[182:183]
	global_store_dwordx4 v[140:141], v[126:129], off
	v_pk_add_f32 v[122:123], v[122:123], v[184:185]
	v_pk_add_f32 v[124:125], v[124:125], v[186:187]
	global_store_dwordx4 v[140:141], v[122:125], off offset:64
	v_pk_add_f32 v[118:119], v[118:119], v[188:189]
	v_pk_add_f32 v[120:121], v[120:121], v[190:191]
	global_store_dwordx4 v[138:139], v[118:121], off
	v_pk_add_f32 v[114:115], v[114:115], v[192:193]
	v_pk_add_f32 v[116:117], v[116:117], v[194:195]
	global_store_dwordx4 v[138:139], v[114:117], off offset:64
	v_pk_add_f32 v[110:111], v[110:111], v[196:197]
	v_pk_add_f32 v[112:113], v[112:113], v[198:199]
	global_store_dwordx4 v[136:137], v[110:113], off
	v_pk_add_f32 v[106:107], v[106:107], v[200:201]
	v_pk_add_f32 v[108:109], v[108:109], v[202:203]
	global_store_dwordx4 v[136:137], v[106:109], off offset:64
	v_pk_add_f32 v[102:103], v[102:103], v[204:205]
	v_pk_add_f32 v[104:105], v[104:105], v[206:207]
	global_store_dwordx4 v[134:135], v[102:105], off
	v_pk_add_f32 v[98:99], v[98:99], v[208:209]
	v_pk_add_f32 v[100:101], v[100:101], v[210:211]
	global_store_dwordx4 v[134:135], v[98:101], off offset:64
	global_load_dwordx4 v[180:183], v[140:141], off offset:512
	global_load_dwordx4 v[184:187], v[140:141], off offset:576
	global_load_dwordx4 v[188:191], v[138:139], off offset:512
	global_load_dwordx4 v[192:195], v[138:139], off offset:576
	global_load_dwordx4 v[196:199], v[136:137], off offset:512
	global_load_dwordx4 v[200:203], v[136:137], off offset:576
	global_load_dwordx4 v[204:207], v[134:135], off offset:512
	global_load_dwordx4 v[208:211], v[134:135], off offset:576
	s_waitcnt vmcnt(0)
	v_pk_add_f32 v[94:95], v[94:95], v[180:181]
	v_pk_add_f32 v[96:97], v[96:97], v[182:183]
	global_store_dwordx4 v[140:141], v[94:97], off offset:512
	v_pk_add_f32 v[90:91], v[90:91], v[184:185]
	v_pk_add_f32 v[92:93], v[92:93], v[186:187]
	global_store_dwordx4 v[140:141], v[90:93], off offset:576
	v_pk_add_f32 v[86:87], v[86:87], v[188:189]
	v_pk_add_f32 v[88:89], v[88:89], v[190:191]
	global_store_dwordx4 v[138:139], v[86:89], off offset:512
	v_pk_add_f32 v[82:83], v[82:83], v[192:193]
	v_pk_add_f32 v[84:85], v[84:85], v[194:195]
	global_store_dwordx4 v[138:139], v[82:85], off offset:576
	v_pk_add_f32 v[78:79], v[78:79], v[196:197]
	v_pk_add_f32 v[80:81], v[80:81], v[198:199]
	global_store_dwordx4 v[136:137], v[78:81], off offset:512
	v_pk_add_f32 v[74:75], v[74:75], v[200:201]
	v_pk_add_f32 v[76:77], v[76:77], v[202:203]
	global_store_dwordx4 v[136:137], v[74:77], off offset:576
	v_pk_add_f32 v[70:71], v[70:71], v[204:205]
	v_pk_add_f32 v[72:73], v[72:73], v[206:207]
	global_store_dwordx4 v[134:135], v[70:73], off offset:512
	v_pk_add_f32 v[66:67], v[66:67], v[208:209]
	v_pk_add_f32 v[68:69], v[68:69], v[210:211]
	global_store_dwordx4 v[134:135], v[66:69], off offset:576
	s_nop 1
	v_add_u32_e32 v66, 0x80, v130
	v_ashrrev_i32_e32 v67, 31, v66
	v_lshlrev_b64 v[66:67], 13, v[66:67]
	v_lshl_add_u64 v[66:67], s[72:73], 0, v[66:67]
	v_lshl_add_u64 v[72:73], v[66:67], 0, v[132:133]
	v_add_u32_e32 v66, 0x90, v130
	v_ashrrev_i32_e32 v67, 31, v66
	v_lshlrev_b64 v[66:67], 13, v[66:67]
	v_lshl_add_u64 v[66:67], s[72:73], 0, v[66:67]
	v_lshl_add_u64 v[70:71], v[66:67], 0, v[132:133]
	v_add_u32_e32 v66, 0xa0, v130
	v_ashrrev_i32_e32 v67, 31, v66
	v_lshlrev_b64 v[66:67], 13, v[66:67]
	v_lshl_add_u64 v[66:67], s[72:73], 0, v[66:67]
	v_lshl_add_u64 v[68:69], v[66:67], 0, v[132:133]
	v_add_u32_e32 v66, 0xb0, v130
	v_ashrrev_i32_e32 v67, 31, v66
	v_lshlrev_b64 v[66:67], 13, v[66:67]
	v_lshl_add_u64 v[66:67], s[72:73], 0, v[66:67]
	v_lshl_add_u64 v[66:67], v[66:67], 0, v[132:133]
	global_load_dwordx4 v[180:183], v[72:73], off
	global_load_dwordx4 v[184:187], v[72:73], off offset:64
	global_load_dwordx4 v[188:191], v[70:71], off
	global_load_dwordx4 v[192:195], v[70:71], off offset:64
	global_load_dwordx4 v[196:199], v[68:69], off
	global_load_dwordx4 v[200:203], v[68:69], off offset:64
	global_load_dwordx4 v[204:207], v[66:67], off
	global_load_dwordx4 v[208:211], v[66:67], off offset:64
	s_waitcnt vmcnt(0)
	v_pk_add_f32 v[62:63], v[62:63], v[180:181]
	v_pk_add_f32 v[64:65], v[64:65], v[182:183]
	global_store_dwordx4 v[72:73], v[62:65], off
	v_pk_add_f32 v[58:59], v[58:59], v[184:185]
	v_pk_add_f32 v[60:61], v[60:61], v[186:187]
	global_store_dwordx4 v[72:73], v[58:61], off offset:64
	v_pk_add_f32 v[54:55], v[54:55], v[188:189]
	v_pk_add_f32 v[56:57], v[56:57], v[190:191]
	global_store_dwordx4 v[70:71], v[54:57], off
	v_pk_add_f32 v[50:51], v[50:51], v[192:193]
	v_pk_add_f32 v[52:53], v[52:53], v[194:195]
	global_store_dwordx4 v[70:71], v[50:53], off offset:64
	v_pk_add_f32 v[46:47], v[46:47], v[196:197]
	v_pk_add_f32 v[48:49], v[48:49], v[198:199]
	global_store_dwordx4 v[68:69], v[46:49], off
	v_pk_add_f32 v[42:43], v[42:43], v[200:201]
	v_pk_add_f32 v[44:45], v[44:45], v[202:203]
	global_store_dwordx4 v[68:69], v[42:45], off offset:64
	v_pk_add_f32 v[38:39], v[38:39], v[204:205]
	v_pk_add_f32 v[40:41], v[40:41], v[206:207]
	global_store_dwordx4 v[66:67], v[38:41], off
	v_pk_add_f32 v[34:35], v[34:35], v[208:209]
	v_pk_add_f32 v[36:37], v[36:37], v[210:211]
	global_store_dwordx4 v[66:67], v[34:37], off offset:64
	global_load_dwordx4 v[180:183], v[72:73], off offset:512
	global_load_dwordx4 v[184:187], v[72:73], off offset:576
	global_load_dwordx4 v[188:191], v[70:71], off offset:512
	global_load_dwordx4 v[192:195], v[70:71], off offset:576
	global_load_dwordx4 v[196:199], v[68:69], off offset:512
	global_load_dwordx4 v[200:203], v[68:69], off offset:576
	global_load_dwordx4 v[204:207], v[66:67], off offset:512
	global_load_dwordx4 v[208:211], v[66:67], off offset:576
	s_waitcnt vmcnt(0)
	v_pk_add_f32 v[30:31], v[30:31], v[180:181]
	v_pk_add_f32 v[32:33], v[32:33], v[182:183]
	global_store_dwordx4 v[72:73], v[30:33], off offset:512
	v_pk_add_f32 v[26:27], v[26:27], v[184:185]
	v_pk_add_f32 v[28:29], v[28:29], v[186:187]
	global_store_dwordx4 v[72:73], v[26:29], off offset:576
	v_pk_add_f32 v[22:23], v[22:23], v[188:189]
	v_pk_add_f32 v[24:25], v[24:25], v[190:191]
	global_store_dwordx4 v[70:71], v[22:25], off offset:512
	v_pk_add_f32 v[18:19], v[18:19], v[192:193]
	v_pk_add_f32 v[20:21], v[20:21], v[194:195]
	global_store_dwordx4 v[70:71], v[18:21], off offset:576
	v_pk_add_f32 v[14:15], v[14:15], v[196:197]
	v_pk_add_f32 v[16:17], v[16:17], v[198:199]
	global_store_dwordx4 v[68:69], v[14:17], off offset:512
	v_pk_add_f32 v[10:11], v[10:11], v[200:201]
	v_pk_add_f32 v[12:13], v[12:13], v[202:203]
	global_store_dwordx4 v[68:69], v[10:13], off offset:576
	v_pk_add_f32 v[6:7], v[6:7], v[204:205]
	v_pk_add_f32 v[8:9], v[8:9], v[206:207]
	global_store_dwordx4 v[66:67], v[6:9], off offset:512
	v_pk_add_f32 v[2:3], v[2:3], v[208:209]
	v_pk_add_f32 v[4:5], v[4:5], v[210:211]
	global_store_dwordx4 v[66:67], v[2:5], off offset:576
	s_and_b64 vcc, exec, s[0:1]
	s_mov_b32 s8, s5
	s_mov_b32 s7, s6
	s_cbranch_vccz .LBB0_29
; #define WAIT_V(n) asm volatile("s_waitcnt vmcnt(" #n ")" ::: "memory")
; #define BAR __builtin_amdgcn_s_barrier()
; template <class EPI>
; DI void gemm_stream(const u16* __restrict__ A, const u16* __restrict__ Bt, const int K, const int nM, const int nN,
;                     const int bid, const int nb, const int tid, EPI epi) {
;     ...
;   WAIT_V(0);
;   if (wr == 0) BAR;
;   BAR;
	s_waitcnt vmcnt(0)
	s_movk_i32 s0, 0x100
	v_cmp_gt_u32_e32 vcc, s0, v239
	s_and_saveexec_b64 s[0:1], vcc
	s_cbranch_execz .LBB0_36
	s_barrier

.LBB0_46:
	v_or_b32_e32 v149, 0x10000, v146
	v_add_u32_e32 v154, 0x10400, v146
	ds_read_b128 v[150:153], v149
	ds_read_b128 v[154:157], v154
	v_add_u32_e32 v149, 0x10800, v146
	v_add_u32_e32 v162, 0x10c00, v146
	ds_read_b128 v[158:161], v149
	ds_read_b128 v[166:169], v162
	s_add_i32 s11, s10, -2
	s_cmp_lt_u32 s11, 30
	s_cselect_b32 s12, s9, s6
	s_cselect_b32 s13, s8, s5
	v_add_u32_e32 v162, 0xc000, v0
	v_add_u32_e32 v149, 0xfffc0000, v148
	v_readfirstlane_b32 s14, v162
	s_mov_b32 m0, s14
	ds_read_b128 v[170:173], v145
	ds_read_b128 v[174:177], v145 offset:1024
	ds_read_b128 v[180:183], v145 offset:2048
	ds_read_b128 v[184:187], v145 offset:3072
	ds_read_b128 v[188:191], v145 offset:4096
	ds_read_b128 v[192:195], v145 offset:5120
	ds_read_b128 v[196:199], v145 offset:6144
	ds_read_b128 v[200:203], v145 offset:7168
	global_load_lds_dwordx4 v149, s[80:81]
	v_add_u32_e32 v149, 0xe000, v0
	s_nop 0
	s_bitset1_b32 m0, 13
	s_nop 0
	global_load_lds_dwordx4 v148, s[80:81]
	s_waitcnt lgkmcnt(8)
	v_or_b32_e32 v149, 0x14000, v146
	v_add_u32_e32 v162, 0x14400, v146
	ds_read_b128 v[204:207], v149
	ds_read_b128 v[208:211], v162
	v_add_u32_e32 v149, 0x14800, v146
	v_add_u32_e32 v162, 0x14c00, v146
	ds_read_b128 v[212:215], v149
	ds_read_b128 v[216:219], v162
	s_waitcnt vmcnt(8)
	s_waitcnt lgkmcnt(0)
	s_barrier
	s_setprio 1
	v_mfma_f32_16x16x32_bf16 v[126:129], v[150:153], v[170:173], v[126:129]
	v_mfma_f32_16x16x32_bf16 v[118:121], v[158:161], v[170:173], v[118:121]
	v_mfma_f32_16x16x32_bf16 v[110:113], v[150:153], v[180:183], v[110:113]
	v_mfma_f32_16x16x32_bf16 v[102:105], v[158:161], v[180:183], v[102:105]
	v_mfma_f32_16x16x32_bf16 v[94:97], v[150:153], v[188:191], v[94:97]
	v_mfma_f32_16x16x32_bf16 v[86:89], v[158:161], v[188:191], v[86:89]
	v_mfma_f32_16x16x32_bf16 v[78:81], v[150:153], v[196:199], v[78:81]
	v_mfma_f32_16x16x32_bf16 v[70:73], v[158:161], v[196:199], v[70:73]
	v_mfma_f32_16x16x32_bf16 v[126:129], v[154:157], v[174:177], v[126:129]
	v_mfma_f32_16x16x32_bf16 v[118:121], v[166:169], v[174:177], v[118:121]
	v_mfma_f32_16x16x32_bf16 v[110:113], v[154:157], v[184:187], v[110:113]
	v_mfma_f32_16x16x32_bf16 v[102:105], v[166:169], v[184:187], v[102:105]
	v_mfma_f32_16x16x32_bf16 v[94:97], v[154:157], v[192:195], v[94:97]
	v_mfma_f32_16x16x32_bf16 v[86:89], v[166:169], v[192:195], v[86:89]
	v_mfma_f32_16x16x32_bf16 v[78:81], v[154:157], v[200:203], v[78:81]
	v_mfma_f32_16x16x32_bf16 v[70:73], v[166:169], v[200:203], v[70:73]
	v_mfma_f32_16x16x32_bf16 v[122:125], v[204:207], v[170:173], v[122:125]
	v_mfma_f32_16x16x32_bf16 v[114:117], v[212:215], v[170:173], v[114:117]
	v_mfma_f32_16x16x32_bf16 v[106:109], v[204:207], v[180:183], v[106:109]
	v_mfma_f32_16x16x32_bf16 v[98:101], v[212:215], v[180:183], v[98:101]
	v_mfma_f32_16x16x32_bf16 v[90:93], v[204:207], v[188:191], v[90:93]
	v_mfma_f32_16x16x32_bf16 v[82:85], v[212:215], v[188:191], v[82:85]
	v_mfma_f32_16x16x32_bf16 v[74:77], v[204:207], v[196:199], v[74:77]
	v_mfma_f32_16x16x32_bf16 v[66:69], v[212:215], v[196:199], v[66:69]
	v_mfma_f32_16x16x32_bf16 v[122:125], v[208:211], v[174:177], v[122:125]
	v_mfma_f32_16x16x32_bf16 v[114:117], v[216:219], v[174:177], v[114:117]
	v_mfma_f32_16x16x32_bf16 v[106:109], v[208:211], v[184:187], v[106:109]
	v_mfma_f32_16x16x32_bf16 v[98:101], v[216:219], v[184:187], v[98:101]
	v_mfma_f32_16x16x32_bf16 v[90:93], v[208:211], v[192:195], v[90:93]
	v_mfma_f32_16x16x32_bf16 v[82:85], v[216:219], v[192:195], v[82:85]
	v_mfma_f32_16x16x32_bf16 v[74:77], v[208:211], v[200:203], v[74:77]
	v_mfma_f32_16x16x32_bf16 v[66:69], v[216:219], v[200:203], v[66:69]
	s_setprio 0
	s_barrier
	s_cselect_b32 s14, s10, 0
	s_lshl_b32 s12, s12, 11
	s_lshl_b32 s15, s14, 6
	s_or_b32 s16, s12, s15
	s_lshl_b32 s16, s16, 1
	v_readfirstlane_b32 s17, v132
	v_add_u32_e32 v149, s16, v130
	s_mov_b32 m0, s17
	s_nop 0
	global_load_lds_dwordx4 v149, s[82:83]
	v_add_u32_e32 v149, s16, v131
	s_bitset1_b32 m0, 13
	s_nop 0
	global_load_lds_dwordx4 v149, s[82:83]
	s_lshl_b32 s16, s13, 11
	s_or_b32 s17, s16, s15
	s_lshl_b32 s17, s17, 1
	v_readfirstlane_b32 s18, v0
	v_add_u32_e32 v149, s17, v130
	s_mov_b32 m0, s18
	ds_read_b128 v[170:173], v145 offset:16384
	ds_read_b128 v[174:177], v145 offset:17408
	ds_read_b128 v[180:183], v145 offset:18432
	ds_read_b128 v[184:187], v145 offset:19456
	ds_read_b128 v[188:191], v145 offset:20480
	ds_read_b128 v[192:195], v145 offset:21504
	ds_read_b128 v[196:199], v145 offset:22528
	ds_read_b128 v[200:203], v145 offset:23552
	global_load_lds_dwordx4 v149, s[80:81]
	v_add_u32_e32 v149, s17, v131
	s_bitset1_b32 m0, 13
	s_nop 0
	global_load_lds_dwordx4 v149, s[80:81]
	s_or_b32 s17, s12, 0x40000
	s_or_b32 s18, s17, s15
	s_lshl_b32 s18, s18, 1
	v_readfirstlane_b32 s19, v135
	v_add_u32_e32 v149, s18, v130
	s_mov_b32 m0, s19
	s_nop 0
	global_load_lds_dwordx4 v149, s[82:83]
	v_add_u32_e32 v149, s18, v131
	s_bitset1_b32 m0, 13
	s_nop 0
	global_load_lds_dwordx4 v149, s[82:83]
	s_waitcnt vmcnt(8)
	s_waitcnt lgkmcnt(0)
	s_barrier
	s_setprio 1
	v_mfma_f32_16x16x32_bf16 v[62:65], v[150:153], v[170:173], v[62:65]
	v_mfma_f32_16x16x32_bf16 v[54:57], v[158:161], v[170:173], v[54:57]
	v_mfma_f32_16x16x32_bf16 v[46:49], v[150:153], v[180:183], v[46:49]
	v_mfma_f32_16x16x32_bf16 v[38:41], v[158:161], v[180:183], v[38:41]
	v_mfma_f32_16x16x32_bf16 v[30:33], v[150:153], v[188:191], v[30:33]
	v_mfma_f32_16x16x32_bf16 v[22:25], v[158:161], v[188:191], v[22:25]
	v_mfma_f32_16x16x32_bf16 v[14:17], v[150:153], v[196:199], v[14:17]
	v_mfma_f32_16x16x32_bf16 v[6:9], v[158:161], v[196:199], v[6:9]
	v_mfma_f32_16x16x32_bf16 v[62:65], v[154:157], v[174:177], v[62:65]
	v_mfma_f32_16x16x32_bf16 v[54:57], v[166:169], v[174:177], v[54:57]
	v_mfma_f32_16x16x32_bf16 v[46:49], v[154:157], v[184:187], v[46:49]
	v_mfma_f32_16x16x32_bf16 v[38:41], v[166:169], v[184:187], v[38:41]
	v_mfma_f32_16x16x32_bf16 v[30:33], v[154:157], v[192:195], v[30:33]
	v_mfma_f32_16x16x32_bf16 v[22:25], v[166:169], v[192:195], v[22:25]
	v_mfma_f32_16x16x32_bf16 v[14:17], v[154:157], v[200:203], v[14:17]
	v_mfma_f32_16x16x32_bf16 v[6:9], v[166:169], v[200:203], v[6:9]
	v_mfma_f32_16x16x32_bf16 v[58:61], v[204:207], v[170:173], v[58:61]
	v_mfma_f32_16x16x32_bf16 v[50:53], v[212:215], v[170:173], v[50:53]
	v_mfma_f32_16x16x32_bf16 v[42:45], v[204:207], v[180:183], v[42:45]
	v_mfma_f32_16x16x32_bf16 v[34:37], v[212:215], v[180:183], v[34:37]
	v_mfma_f32_16x16x32_bf16 v[26:29], v[204:207], v[188:191], v[26:29]
	v_mfma_f32_16x16x32_bf16 v[18:21], v[212:215], v[188:191], v[18:21]
	v_mfma_f32_16x16x32_bf16 v[10:13], v[204:207], v[196:199], v[10:13]
	v_mfma_f32_16x16x32_bf16 v[2:5], v[212:215], v[196:199], v[2:5]
	v_mfma_f32_16x16x32_bf16 v[58:61], v[208:211], v[174:177], v[58:61]
	v_mfma_f32_16x16x32_bf16 v[50:53], v[216:219], v[174:177], v[50:53]
	v_mfma_f32_16x16x32_bf16 v[42:45], v[208:211], v[184:187], v[42:45]
	v_mfma_f32_16x16x32_bf16 v[34:37], v[216:219], v[184:187], v[34:37]
	v_mfma_f32_16x16x32_bf16 v[26:29], v[208:211], v[192:195], v[26:29]
	v_mfma_f32_16x16x32_bf16 v[18:21], v[216:219], v[192:195], v[18:21]
	v_mfma_f32_16x16x32_bf16 v[10:13], v[208:211], v[200:203], v[10:13]
	v_mfma_f32_16x16x32_bf16 v[2:5], v[216:219], v[200:203], v[2:5]
	s_setprio 0
	s_barrier
	v_or_b32_e32 v149, 0x18000, v146
	v_add_u32_e32 v154, 0x18400, v146
	ds_read_b128 v[150:153], v149
	ds_read_b128 v[154:157], v154
	v_add_u32_e32 v149, 0x18800, v146
	v_add_u32_e32 v162, 0x18c00, v146
	ds_read_b128 v[158:161], v149
	ds_read_b128 v[166:169], v162
	s_lshl_b32 s13, s13, 12
	s_lshl_b32 s14, s14, 7
	s_add_i32 s13, s14, s13
	s_add_i32 s13, s13, 0x80000
	v_readfirstlane_b32 s14, v137
	v_add_u32_e32 v149, s13, v130
	s_mov_b32 m0, s14
	ds_read_b128 v[170:173], v145 offset:32768
	ds_read_b128 v[174:177], v145 offset:33792
	ds_read_b128 v[180:183], v145 offset:34816
	ds_read_b128 v[184:187], v145 offset:35840
	ds_read_b128 v[188:191], v145 offset:36864
	ds_read_b128 v[192:195], v145 offset:37888
	ds_read_b128 v[196:199], v145 offset:38912
	ds_read_b128 v[200:203], v145 offset:39936
	global_load_lds_dwordx4 v149, s[80:81]
	v_add_u32_e32 v149, s13, v131
	s_bitset1_b32 m0, 13
	s_nop 0
	global_load_lds_dwordx4 v149, s[80:81]
	s_waitcnt lgkmcnt(8)
	v_or_b32_e32 v149, 0x1c000, v146
	v_add_u32_e32 v162, 0x1c400, v146
	ds_read_b128 v[204:207], v149
	ds_read_b128 v[208:211], v162
	v_add_u32_e32 v149, 0x1c800, v146
	v_add_u32_e32 v162, 0x1cc00, v146
	ds_read_b128 v[212:215], v149
	ds_read_b128 v[216:219], v162
	s_waitcnt vmcnt(8)
	s_waitcnt lgkmcnt(0)
	s_barrier
	s_setprio 1
	v_mfma_f32_16x16x32_bf16 v[126:129], v[150:153], v[170:173], v[126:129]
	v_mfma_f32_16x16x32_bf16 v[118:121], v[158:161], v[170:173], v[118:121]
	v_mfma_f32_16x16x32_bf16 v[110:113], v[150:153], v[180:183], v[110:113]
	v_mfma_f32_16x16x32_bf16 v[102:105], v[158:161], v[180:183], v[102:105]
	v_mfma_f32_16x16x32_bf16 v[94:97], v[150:153], v[188:191], v[94:97]
	v_mfma_f32_16x16x32_bf16 v[86:89], v[158:161], v[188:191], v[86:89]
	v_mfma_f32_16x16x32_bf16 v[78:81], v[150:153], v[196:199], v[78:81]
	v_mfma_f32_16x16x32_bf16 v[70:73], v[158:161], v[196:199], v[70:73]
	v_mfma_f32_16x16x32_bf16 v[126:129], v[154:157], v[174:177], v[126:129]
	v_mfma_f32_16x16x32_bf16 v[118:121], v[166:169], v[174:177], v[118:121]
	v_mfma_f32_16x16x32_bf16 v[110:113], v[154:157], v[184:187], v[110:113]
	v_mfma_f32_16x16x32_bf16 v[102:105], v[166:169], v[184:187], v[102:105]
	v_mfma_f32_16x16x32_bf16 v[94:97], v[154:157], v[192:195], v[94:97]
	v_mfma_f32_16x16x32_bf16 v[86:89], v[166:169], v[192:195], v[86:89]
	v_mfma_f32_16x16x32_bf16 v[78:81], v[154:157], v[200:203], v[78:81]
	v_mfma_f32_16x16x32_bf16 v[70:73], v[166:169], v[200:203], v[70:73]
	v_mfma_f32_16x16x32_bf16 v[122:125], v[204:207], v[170:173], v[122:125]
	v_mfma_f32_16x16x32_bf16 v[114:117], v[212:215], v[170:173], v[114:117]
	v_mfma_f32_16x16x32_bf16 v[106:109], v[204:207], v[180:183], v[106:109]
	v_mfma_f32_16x16x32_bf16 v[98:101], v[212:215], v[180:183], v[98:101]
	v_mfma_f32_16x16x32_bf16 v[90:93], v[204:207], v[188:191], v[90:93]
	v_mfma_f32_16x16x32_bf16 v[82:85], v[212:215], v[188:191], v[82:85]
	v_mfma_f32_16x16x32_bf16 v[74:77], v[204:207], v[196:199], v[74:77]
	v_mfma_f32_16x16x32_bf16 v[66:69], v[212:215], v[196:199], v[66:69]
	v_mfma_f32_16x16x32_bf16 v[122:125], v[208:211], v[174:177], v[122:125]
	v_mfma_f32_16x16x32_bf16 v[114:117], v[216:219], v[174:177], v[114:117]
	v_mfma_f32_16x16x32_bf16 v[106:109], v[208:211], v[184:187], v[106:109]
	v_mfma_f32_16x16x32_bf16 v[98:101], v[216:219], v[184:187], v[98:101]
	v_mfma_f32_16x16x32_bf16 v[90:93], v[208:211], v[192:195], v[90:93]
	v_mfma_f32_16x16x32_bf16 v[82:85], v[216:219], v[192:195], v[82:85]
	v_mfma_f32_16x16x32_bf16 v[74:77], v[208:211], v[200:203], v[74:77]
	v_mfma_f32_16x16x32_bf16 v[66:69], v[216:219], v[200:203], v[66:69]
	s_setprio 0
	s_barrier
; DI float sigmoidf_(float v) { return __builtin_amdgcn_rcpf(1.f + __expf(-v)); }
; #define EPI_SCHED __builtin_amdgcn_sched_barrier(0)
; DI void gemm_gateup(const Params& p, int bid, int nb, int tid) {
;     ...
;     _Pragma("unroll") for (int ai = 0; ai < 2; ++ai) _Pragma("unroll") for (int m = 0; m < 4; ++m) _Pragma("unroll") for (int n = 0; n < 2; ++n) {
;       const int col = pn * 128 + wc * 32 + n * 16 + fq * 4;
;       const int row = brow + ai * HALF + wr * 64 + m * 16 + fr;
;       const f32x4 g = acc[ai][0][m][n], uu = acc[ai][1][m][n];
;       uint2 w;
;       w.x = pk2(g[0] * sigmoidf_(g[0]) * uu[0], g[1] * sigmoidf_(g[1]) * uu[1]);
;       w.y = pk2(g[2] * sigmoidf_(g[2]) * uu[2], g[3] * sigmoidf_(g[3]) * uu[3]);
;       *reinterpret_cast<uint2*>(C + (size_t)row * DFF + col) = w;
;       EPI_SCHED;
;     }
	s_or_b32 s13, s15, 64
	s_or_b32 s12, s13, s12
	s_lshl_b32 s12, s12, 1
	v_readfirstlane_b32 s14, v139
	v_add_u32_e32 v149, s12, v130
	s_mov_b32 m0, s14
	s_nop 0
	global_load_lds_dwordx4 v149, s[82:83]
	v_add_u32_e32 v149, s12, v131
	s_bitset1_b32 m0, 13
	s_nop 0
	global_load_lds_dwordx4 v149, s[82:83]
	s_or_b32 s12, s13, s16
	s_lshl_b32 s12, s12, 1
	v_readfirstlane_b32 s14, v141
	v_add_u32_e32 v149, s12, v130
	s_mov_b32 m0, s14
	ds_read_b128 v[170:173], v145 offset:49152
	ds_read_b128 v[174:177], v145 offset:50176
	ds_read_b128 v[180:183], v145 offset:51200
	ds_read_b128 v[184:187], v145 offset:52224
	ds_read_b128 v[188:191], v145 offset:53248
	ds_read_b128 v[192:195], v145 offset:54272
	ds_read_b128 v[196:199], v145 offset:55296
	ds_read_b128 v[200:203], v145 offset:56320
	global_load_lds_dwordx4 v149, s[80:81]
	v_add_u32_e32 v149, s12, v131
	s_bitset1_b32 m0, 13
	s_nop 0
	global_load_lds_dwordx4 v149, s[80:81]
	s_or_b32 s12, s17, s13
	s_lshl_b32 s12, s12, 1
	v_readfirstlane_b32 s13, v143
	v_add_u32_e32 v149, s12, v130
	s_mov_b32 m0, s13
	s_nop 0
	global_load_lds_dwordx4 v149, s[82:83]
	v_add_u32_e32 v149, s12, v131
	s_bitset1_b32 m0, 13
	s_nop 0
	global_load_lds_dwordx4 v149, s[82:83]
	s_waitcnt vmcnt(8)
	s_waitcnt lgkmcnt(0)
	s_barrier
	s_setprio 1
	v_mfma_f32_16x16x32_bf16 v[62:65], v[150:153], v[170:173], v[62:65]
	v_mfma_f32_16x16x32_bf16 v[54:57], v[158:161], v[170:173], v[54:57]
	v_mfma_f32_16x16x32_bf16 v[46:49], v[150:153], v[180:183], v[46:49]
	v_mfma_f32_16x16x32_bf16 v[38:41], v[158:161], v[180:183], v[38:41]
	v_mfma_f32_16x16x32_bf16 v[30:33], v[150:153], v[188:191], v[30:33]
	v_mfma_f32_16x16x32_bf16 v[22:25], v[158:161], v[188:191], v[22:25]
	v_mfma_f32_16x16x32_bf16 v[14:17], v[150:153], v[196:199], v[14:17]
	v_mfma_f32_16x16x32_bf16 v[6:9], v[158:161], v[196:199], v[6:9]
	v_mfma_f32_16x16x32_bf16 v[62:65], v[154:157], v[174:177], v[62:65]
	v_mfma_f32_16x16x32_bf16 v[54:57], v[166:169], v[174:177], v[54:57]
	v_mfma_f32_16x16x32_bf16 v[46:49], v[154:157], v[184:187], v[46:49]
	v_mfma_f32_16x16x32_bf16 v[38:41], v[166:169], v[184:187], v[38:41]
	v_mfma_f32_16x16x32_bf16 v[30:33], v[154:157], v[192:195], v[30:33]
	v_mfma_f32_16x16x32_bf16 v[22:25], v[166:169], v[192:195], v[22:25]
	v_mfma_f32_16x16x32_bf16 v[14:17], v[154:157], v[200:203], v[14:17]
	v_mfma_f32_16x16x32_bf16 v[6:9], v[166:169], v[200:203], v[6:9]
	v_mfma_f32_16x16x32_bf16 v[58:61], v[204:207], v[170:173], v[58:61]
	v_mfma_f32_16x16x32_bf16 v[50:53], v[212:215], v[170:173], v[50:53]
	v_mfma_f32_16x16x32_bf16 v[42:45], v[204:207], v[180:183], v[42:45]
	v_mfma_f32_16x16x32_bf16 v[34:37], v[212:215], v[180:183], v[34:37]
	v_mfma_f32_16x16x32_bf16 v[26:29], v[204:207], v[188:191], v[26:29]
	v_mfma_f32_16x16x32_bf16 v[18:21], v[212:215], v[188:191], v[18:21]
	v_mfma_f32_16x16x32_bf16 v[10:13], v[204:207], v[196:199], v[10:13]
	v_mfma_f32_16x16x32_bf16 v[2:5], v[212:215], v[196:199], v[2:5]
	v_mfma_f32_16x16x32_bf16 v[58:61], v[208:211], v[174:177], v[58:61]
	v_mfma_f32_16x16x32_bf16 v[50:53], v[216:219], v[174:177], v[50:53]
	v_mfma_f32_16x16x32_bf16 v[42:45], v[208:211], v[184:187], v[42:45]
	v_mfma_f32_16x16x32_bf16 v[34:37], v[216:219], v[184:187], v[34:37]
	v_mfma_f32_16x16x32_bf16 v[26:29], v[208:211], v[192:195], v[26:29]
	v_mfma_f32_16x16x32_bf16 v[18:21], v[216:219], v[192:195], v[18:21]
	v_mfma_f32_16x16x32_bf16 v[10:13], v[208:211], v[200:203], v[10:13]
	v_mfma_f32_16x16x32_bf16 v[2:5], v[216:219], v[200:203], v[2:5]
	s_setprio 0
	s_add_i32 s10, s10, 2
	s_cmp_gt_u32 s11, 29
	v_add_u32_e32 v148, 0x100, v148
	s_barrier
	s_cbranch_scc0 .LBB0_46
	v_mov_b32_e32 v148, v239
	s_lshl_b32 s7, s7, 7
	v_lshrrev_b32_e32 v149, 1, v148
	v_lshrrev_b32_e32 v150, 2, v148
	v_and_b32_e32 v149, 0x60, v149
	v_and_b32_e32 v150, 12, v150
	v_or3_b32 v150, v149, s7, v150
	v_ashrrev_i32_e32 v149, 2, v148
	v_and_b32_e32 v149, 0xffffffc0, v149
	v_and_or_b32 v148, v148, 15, s8
	v_add_u32_e32 v148, v148, v149
	v_mul_f32_e32 v149, 0xbfb8aa3b, v126
	v_exp_f32_e32 v149, v149
	s_movk_i32 s7, 0x2c00
	v_ashrrev_i32_e32 v151, 31, v150
	v_add_f32_e32 v149, 1.0, v149
	v_rcp_f32_e32 v152, v149
	v_mul_f32_e32 v149, 0xbfb8aa3b, v127
	v_exp_f32_e32 v149, v149
	s_nop 0
	v_add_f32_e32 v149, 1.0, v149
	v_rcp_f32_e32 v153, v149
	s_nop 0
	v_pk_mul_f32 v[126:127], v[126:127], v[152:153]
	s_nop 0
	v_pk_mul_f32 v[122:123], v[126:127], v[122:123]
	s_nop 0
	v_cvt_pk_bf16_f32 v126, v122, v123
	v_mul_f32_e32 v122, 0xbfb8aa3b, v128
	v_mul_f32_e32 v123, 0xbfb8aa3b, v129
	v_exp_f32_e32 v122, v122
	v_exp_f32_e32 v123, v123
	v_add_f32_e32 v122, 1.0, v122
	v_add_f32_e32 v123, 1.0, v123
	v_rcp_f32_e32 v122, v122
	v_rcp_f32_e32 v123, v123
	s_nop 0
	v_pk_mul_f32 v[122:123], v[128:129], v[122:123]
	s_nop 0
	v_pk_mul_f32 v[122:123], v[122:123], v[124:125]
	v_lshlrev_b64 v[124:125], 1, v[150:151]
	v_cvt_pk_bf16_f32 v127, v122, v123
	v_mov_b64_e32 v[122:123], s[76:77]
	v_mad_i64_i32 v[128:129], s[8:9], v148, s7, v[122:123]
	v_lshl_add_u64 v[128:129], v[128:129], 0, v[124:125]
	global_store_dwordx2 v[128:129], v[126:127], off
	v_mul_f32_e32 v126, 0xbfb8aa3b, v118
	v_mul_f32_e32 v127, 0xbfb8aa3b, v119
	v_exp_f32_e32 v126, v126
	v_exp_f32_e32 v127, v127
	v_add_f32_e32 v126, 1.0, v126
	v_add_f32_e32 v127, 1.0, v127
	v_rcp_f32_e32 v126, v126
	v_rcp_f32_e32 v127, v127
	s_nop 0
	v_pk_mul_f32 v[118:119], v[118:119], v[126:127]
	s_nop 0
	v_pk_mul_f32 v[114:115], v[118:119], v[114:115]
	s_nop 0
	v_cvt_pk_bf16_f32 v114, v114, v115
	v_mul_f32_e32 v115, 0xbfb8aa3b, v120
	v_exp_f32_e32 v115, v115
	s_nop 0
	v_add_f32_e32 v115, 1.0, v115
	v_rcp_f32_e32 v118, v115
	v_mul_f32_e32 v115, 0xbfb8aa3b, v121
	v_exp_f32_e32 v115, v115
	s_nop 0
; #define EPI_SCHED __builtin_amdgcn_sched_barrier(0)
; DI float sigmoidf_(float v) { return __builtin_amdgcn_rcpf(1.f + __expf(-v)); }
; DI void gemm_gateup(const Params& p, int bid, int nb, int tid) {
;     ...
;     _Pragma("unroll") for (int ai = 0; ai < 2; ++ai) _Pragma("unroll") for (int m = 0; m < 4; ++m) _Pragma("unroll") for (int n = 0; n < 2; ++n) {
;       const int col = pn * 128 + wc * 32 + n * 16 + fq * 4;
;       const int row = brow + ai * HALF + wr * 64 + m * 16 + fr;
;       const f32x4 g = acc[ai][0][m][n], uu = acc[ai][1][m][n];
;       uint2 w;
;       w.x = pk2(g[0] * sigmoidf_(g[0]) * uu[0], g[1] * sigmoidf_(g[1]) * uu[1]);
;       w.y = pk2(g[2] * sigmoidf_(g[2]) * uu[2], g[3] * sigmoidf_(g[3]) * uu[3]);
;       *reinterpret_cast<uint2*>(C + (size_t)row * DFF + col) = w;
;       EPI_SCHED;
;     }
	v_add_f32_e32 v115, 1.0, v115
	v_rcp_f32_e32 v119, v115
	s_nop 0
	v_pk_mul_f32 v[118:119], v[120:121], v[118:119]
	s_nop 0
	v_pk_mul_f32 v[116:117], v[118:119], v[116:117]
	s_nop 0
	v_cvt_pk_bf16_f32 v115, v116, v117
	global_store_dwordx2 v[128:129], v[114:115], off offset:32
	v_mul_f32_e32 v114, 0xbfb8aa3b, v110
	v_mul_f32_e32 v115, 0xbfb8aa3b, v111
	v_exp_f32_e32 v114, v114
	v_exp_f32_e32 v115, v115
	v_or_b32_e32 v116, 16, v148
	v_add_f32_e32 v114, 1.0, v114
	v_add_f32_e32 v115, 1.0, v115
	v_rcp_f32_e32 v114, v114
	v_rcp_f32_e32 v115, v115
	s_nop 0
	v_pk_mul_f32 v[110:111], v[110:111], v[114:115]
	s_nop 0
	v_pk_mul_f32 v[106:107], v[110:111], v[106:107]
	s_nop 0
	v_cvt_pk_bf16_f32 v106, v106, v107
	v_mul_f32_e32 v107, 0xbfb8aa3b, v112
	v_exp_f32_e32 v107, v107
	s_nop 0
	v_add_f32_e32 v107, 1.0, v107
	v_rcp_f32_e32 v110, v107
	v_mul_f32_e32 v107, 0xbfb8aa3b, v113
	v_exp_f32_e32 v107, v107
	s_nop 0
	v_add_f32_e32 v107, 1.0, v107
	v_rcp_f32_e32 v111, v107
	s_nop 0
	v_pk_mul_f32 v[110:111], v[112:113], v[110:111]
	s_nop 0
	v_pk_mul_f32 v[108:109], v[110:111], v[108:109]
	s_nop 0
	v_cvt_pk_bf16_f32 v107, v108, v109
	v_mad_i64_i32 v[108:109], s[8:9], v116, s7, v[122:123]
	v_lshl_add_u64 v[108:109], v[108:109], 0, v[124:125]
	global_store_dwordx2 v[108:109], v[106:107], off
	v_mul_f32_e32 v106, 0xbfb8aa3b, v102
	v_mul_f32_e32 v107, 0xbfb8aa3b, v103
	v_exp_f32_e32 v106, v106
	v_exp_f32_e32 v107, v107
	v_add_f32_e32 v106, 1.0, v106
	v_add_f32_e32 v107, 1.0, v107
	v_rcp_f32_e32 v106, v106
	v_rcp_f32_e32 v107, v107
	s_nop 0
	v_pk_mul_f32 v[102:103], v[102:103], v[106:107]
	s_nop 0
	v_pk_mul_f32 v[98:99], v[102:103], v[98:99]
	s_nop 0
	v_cvt_pk_bf16_f32 v98, v98, v99
	v_mul_f32_e32 v99, 0xbfb8aa3b, v104
	v_exp_f32_e32 v99, v99
	s_nop 0
	v_add_f32_e32 v99, 1.0, v99
	v_rcp_f32_e32 v102, v99
	v_mul_f32_e32 v99, 0xbfb8aa3b, v105
	v_exp_f32_e32 v99, v99
	s_nop 0
	v_add_f32_e32 v99, 1.0, v99
	v_rcp_f32_e32 v103, v99
	s_nop 0
	v_pk_mul_f32 v[102:103], v[104:105], v[102:103]
	s_nop 0
	v_pk_mul_f32 v[100:101], v[102:103], v[100:101]
	s_nop 0
	v_cvt_pk_bf16_f32 v99, v100, v101
	global_store_dwordx2 v[108:109], v[98:99], off offset:32
	v_mul_f32_e32 v98, 0xbfb8aa3b, v94
	v_mul_f32_e32 v99, 0xbfb8aa3b, v95
	v_exp_f32_e32 v98, v98
	v_exp_f32_e32 v99, v99
	v_or_b32_e32 v100, 32, v148
	v_add_f32_e32 v98, 1.0, v98
	v_add_f32_e32 v99, 1.0, v99
	v_rcp_f32_e32 v98, v98
	v_rcp_f32_e32 v99, v99
	s_nop 0
	v_pk_mul_f32 v[94:95], v[94:95], v[98:99]
	s_nop 0
	v_pk_mul_f32 v[90:91], v[94:95], v[90:91]
	s_nop 0
	v_cvt_pk_bf16_f32 v90, v90, v91
	v_mul_f32_e32 v91, 0xbfb8aa3b, v96
	v_exp_f32_e32 v91, v91
	s_nop 0
	v_add_f32_e32 v91, 1.0, v91
	v_rcp_f32_e32 v94, v91
	v_mul_f32_e32 v91, 0xbfb8aa3b, v97
	v_exp_f32_e32 v91, v91
	s_nop 0
	v_add_f32_e32 v91, 1.0, v91
	v_rcp_f32_e32 v95, v91
	s_nop 0
	v_pk_mul_f32 v[94:95], v[96:97], v[94:95]
	s_nop 0
	v_pk_mul_f32 v[92:93], v[94:95], v[92:93]
	s_nop 0
	v_cvt_pk_bf16_f32 v91, v92, v93
	v_mad_i64_i32 v[92:93], s[8:9], v100, s7, v[122:123]
	v_lshl_add_u64 v[92:93], v[92:93], 0, v[124:125]
	global_store_dwordx2 v[92:93], v[90:91], off
	v_mul_f32_e32 v90, 0xbfb8aa3b, v86
	v_mul_f32_e32 v91, 0xbfb8aa3b, v87
	v_exp_f32_e32 v90, v90
	v_exp_f32_e32 v91, v91
	v_add_f32_e32 v90, 1.0, v90
	v_add_f32_e32 v91, 1.0, v91
	v_rcp_f32_e32 v90, v90
	v_rcp_f32_e32 v91, v91
	s_nop 0
	v_pk_mul_f32 v[86:87], v[86:87], v[90:91]
	s_nop 0
	v_pk_mul_f32 v[82:83], v[86:87], v[82:83]
	s_nop 0
	v_cvt_pk_bf16_f32 v82, v82, v83
	v_mul_f32_e32 v83, 0xbfb8aa3b, v88
	v_exp_f32_e32 v83, v83
	s_nop 0
	v_add_f32_e32 v83, 1.0, v83
	v_rcp_f32_e32 v86, v83
	v_mul_f32_e32 v83, 0xbfb8aa3b, v89
	v_exp_f32_e32 v83, v83
	s_nop 0
	v_add_f32_e32 v83, 1.0, v83
	v_rcp_f32_e32 v87, v83
	s_nop 0
	v_pk_mul_f32 v[86:87], v[88:89], v[86:87]
	s_nop 0
	v_pk_mul_f32 v[84:85], v[86:87], v[84:85]
	s_nop 0
	v_cvt_pk_bf16_f32 v83, v84, v85
	global_store_dwordx2 v[92:93], v[82:83], off offset:32
	v_mul_f32_e32 v82, 0xbfb8aa3b, v78
	v_mul_f32_e32 v83, 0xbfb8aa3b, v79
	v_exp_f32_e32 v82, v82
	v_exp_f32_e32 v83, v83
	v_or_b32_e32 v84, 48, v148
	v_add_f32_e32 v82, 1.0, v82
	v_add_f32_e32 v83, 1.0, v83
	v_rcp_f32_e32 v82, v82
	v_rcp_f32_e32 v83, v83
	s_nop 0
	v_pk_mul_f32 v[78:79], v[78:79], v[82:83]
	s_nop 0
	v_pk_mul_f32 v[74:75], v[78:79], v[74:75]
	s_nop 0
	v_cvt_pk_bf16_f32 v74, v74, v75
	v_mul_f32_e32 v75, 0xbfb8aa3b, v80
	v_exp_f32_e32 v75, v75
	s_nop 0
	v_add_f32_e32 v75, 1.0, v75
	v_rcp_f32_e32 v78, v75
	v_mul_f32_e32 v75, 0xbfb8aa3b, v81
	v_exp_f32_e32 v75, v75
	s_nop 0
	v_add_f32_e32 v75, 1.0, v75
	v_rcp_f32_e32 v79, v75
	s_nop 0
	v_pk_mul_f32 v[78:79], v[80:81], v[78:79]
	s_nop 0
	v_pk_mul_f32 v[76:77], v[78:79], v[76:77]
	s_nop 0
	v_cvt_pk_bf16_f32 v75, v76, v77
	v_mad_i64_i32 v[76:77], s[8:9], v84, s7, v[122:123]
	v_lshl_add_u64 v[76:77], v[76:77], 0, v[124:125]
	global_store_dwordx2 v[76:77], v[74:75], off
	v_mul_f32_e32 v74, 0xbfb8aa3b, v70
	v_mul_f32_e32 v75, 0xbfb8aa3b, v71
	v_exp_f32_e32 v74, v74
	v_exp_f32_e32 v75, v75
	v_add_f32_e32 v74, 1.0, v74
	v_add_f32_e32 v75, 1.0, v75
	v_rcp_f32_e32 v74, v74
	v_rcp_f32_e32 v75, v75
	s_nop 0
	v_pk_mul_f32 v[70:71], v[70:71], v[74:75]
	s_nop 0
	v_pk_mul_f32 v[66:67], v[70:71], v[66:67]
	s_nop 0
	v_cvt_pk_bf16_f32 v66, v66, v67
	v_mul_f32_e32 v67, 0xbfb8aa3b, v72
	v_exp_f32_e32 v67, v67
	s_nop 0
	v_add_f32_e32 v67, 1.0, v67
	v_rcp_f32_e32 v70, v67
	v_mul_f32_e32 v67, 0xbfb8aa3b, v73
	v_exp_f32_e32 v67, v67
	s_nop 0
	v_add_f32_e32 v67, 1.0, v67
	v_rcp_f32_e32 v71, v67
	s_nop 0
	v_pk_mul_f32 v[70:71], v[72:73], v[70:71]
	s_nop 0
	v_pk_mul_f32 v[68:69], v[70:71], v[68:69]
	s_nop 0
	v_cvt_pk_bf16_f32 v67, v68, v69
; #define EPI_SCHED __builtin_amdgcn_sched_barrier(0)
; DI float sigmoidf_(float v) { return __builtin_amdgcn_rcpf(1.f + __expf(-v)); }
; DI void gemm_gateup(const Params& p, int bid, int nb, int tid) {
;     ...
;     _Pragma("unroll") for (int ai = 0; ai < 2; ++ai) _Pragma("unroll") for (int m = 0; m < 4; ++m) _Pragma("unroll") for (int n = 0; n < 2; ++n) {
;       const int col = pn * 128 + wc * 32 + n * 16 + fq * 4;
;       const int row = brow + ai * HALF + wr * 64 + m * 16 + fr;
;       const f32x4 g = acc[ai][0][m][n], uu = acc[ai][1][m][n];
;       uint2 w;
;       w.x = pk2(g[0] * sigmoidf_(g[0]) * uu[0], g[1] * sigmoidf_(g[1]) * uu[1]);
;       w.y = pk2(g[2] * sigmoidf_(g[2]) * uu[2], g[3] * sigmoidf_(g[3]) * uu[3]);
;       *reinterpret_cast<uint2*>(C + (size_t)row * DFF + col) = w;
;       EPI_SCHED;
;     }
	global_store_dwordx2 v[76:77], v[66:67], off offset:32
	v_mul_f32_e32 v66, 0xbfb8aa3b, v62
	v_mul_f32_e32 v67, 0xbfb8aa3b, v63
	v_exp_f32_e32 v66, v66
	v_exp_f32_e32 v67, v67
	v_add_u32_e32 v68, 0x80, v148
	v_add_f32_e32 v66, 1.0, v66
	v_add_f32_e32 v67, 1.0, v67
	v_rcp_f32_e32 v66, v66
	v_rcp_f32_e32 v67, v67
	s_nop 0
	v_pk_mul_f32 v[62:63], v[62:63], v[66:67]
	s_nop 0
	v_pk_mul_f32 v[58:59], v[62:63], v[58:59]
	s_nop 0
	v_cvt_pk_bf16_f32 v58, v58, v59
	v_mul_f32_e32 v59, 0xbfb8aa3b, v64
	v_exp_f32_e32 v59, v59
	s_nop 0
	v_add_f32_e32 v59, 1.0, v59
	v_rcp_f32_e32 v62, v59
	v_mul_f32_e32 v59, 0xbfb8aa3b, v65
	v_exp_f32_e32 v59, v59
	s_nop 0
	v_add_f32_e32 v59, 1.0, v59
	v_rcp_f32_e32 v63, v59
	s_nop 0
	v_pk_mul_f32 v[62:63], v[64:65], v[62:63]
	s_nop 0
	v_pk_mul_f32 v[60:61], v[62:63], v[60:61]
	s_nop 0
	v_cvt_pk_bf16_f32 v59, v60, v61
	v_mad_i64_i32 v[60:61], s[8:9], v68, s7, v[122:123]
	v_lshl_add_u64 v[60:61], v[60:61], 0, v[124:125]
	global_store_dwordx2 v[60:61], v[58:59], off
	v_mul_f32_e32 v58, 0xbfb8aa3b, v54
	v_mul_f32_e32 v59, 0xbfb8aa3b, v55
	v_exp_f32_e32 v58, v58
	v_exp_f32_e32 v59, v59
	v_add_f32_e32 v58, 1.0, v58
	v_add_f32_e32 v59, 1.0, v59
	v_rcp_f32_e32 v58, v58
	v_rcp_f32_e32 v59, v59
	s_nop 0
	v_pk_mul_f32 v[54:55], v[54:55], v[58:59]
	s_nop 0
	v_pk_mul_f32 v[50:51], v[54:55], v[50:51]
	s_nop 0
	v_cvt_pk_bf16_f32 v50, v50, v51
	v_mul_f32_e32 v51, 0xbfb8aa3b, v56
	v_exp_f32_e32 v51, v51
	s_nop 0
	v_add_f32_e32 v51, 1.0, v51
	v_rcp_f32_e32 v54, v51
	v_mul_f32_e32 v51, 0xbfb8aa3b, v57
	v_exp_f32_e32 v51, v51
	s_nop 0
	v_add_f32_e32 v51, 1.0, v51
	v_rcp_f32_e32 v55, v51
	s_nop 0
	v_pk_mul_f32 v[54:55], v[56:57], v[54:55]
	s_nop 0
	v_pk_mul_f32 v[52:53], v[54:55], v[52:53]
	s_nop 0
	v_cvt_pk_bf16_f32 v51, v52, v53
	global_store_dwordx2 v[60:61], v[50:51], off offset:32
	v_mul_f32_e32 v50, 0xbfb8aa3b, v46
	v_mul_f32_e32 v51, 0xbfb8aa3b, v47
	v_exp_f32_e32 v50, v50
	v_exp_f32_e32 v51, v51
	v_add_u32_e32 v52, 0x90, v148
	v_add_f32_e32 v50, 1.0, v50
	v_add_f32_e32 v51, 1.0, v51
	v_rcp_f32_e32 v50, v50
	v_rcp_f32_e32 v51, v51
	s_nop 0
	v_pk_mul_f32 v[46:47], v[46:47], v[50:51]
	s_nop 0
	v_pk_mul_f32 v[42:43], v[46:47], v[42:43]
	s_nop 0
	v_cvt_pk_bf16_f32 v42, v42, v43
	v_mul_f32_e32 v43, 0xbfb8aa3b, v48
	v_exp_f32_e32 v43, v43
	s_nop 0
	v_add_f32_e32 v43, 1.0, v43
	v_rcp_f32_e32 v46, v43
	v_mul_f32_e32 v43, 0xbfb8aa3b, v49
	v_exp_f32_e32 v43, v43
	s_nop 0
	v_add_f32_e32 v43, 1.0, v43
	v_rcp_f32_e32 v47, v43
	s_nop 0
	v_pk_mul_f32 v[46:47], v[48:49], v[46:47]
	s_nop 0
	v_pk_mul_f32 v[44:45], v[46:47], v[44:45]
	s_nop 0
	v_cvt_pk_bf16_f32 v43, v44, v45
	v_mad_i64_i32 v[44:45], s[8:9], v52, s7, v[122:123]
	v_lshl_add_u64 v[44:45], v[44:45], 0, v[124:125]
	global_store_dwordx2 v[44:45], v[42:43], off
	v_mul_f32_e32 v42, 0xbfb8aa3b, v38
	v_mul_f32_e32 v43, 0xbfb8aa3b, v39
	v_exp_f32_e32 v42, v42
	v_exp_f32_e32 v43, v43
	v_add_f32_e32 v42, 1.0, v42
	v_add_f32_e32 v43, 1.0, v43
	v_rcp_f32_e32 v42, v42
	v_rcp_f32_e32 v43, v43
	s_nop 0
	v_pk_mul_f32 v[38:39], v[38:39], v[42:43]
	s_nop 0
	v_pk_mul_f32 v[34:35], v[38:39], v[34:35]
	s_nop 0
	v_cvt_pk_bf16_f32 v34, v34, v35
	v_mul_f32_e32 v35, 0xbfb8aa3b, v40
	v_exp_f32_e32 v35, v35
	s_nop 0
	v_add_f32_e32 v35, 1.0, v35
	v_rcp_f32_e32 v38, v35
	v_mul_f32_e32 v35, 0xbfb8aa3b, v41
	v_exp_f32_e32 v35, v35
	s_nop 0
	v_add_f32_e32 v35, 1.0, v35
	v_rcp_f32_e32 v39, v35
	s_nop 0
	v_pk_mul_f32 v[38:39], v[40:41], v[38:39]
	s_nop 0
	v_pk_mul_f32 v[36:37], v[38:39], v[36:37]
	s_nop 0
	v_cvt_pk_bf16_f32 v35, v36, v37
	global_store_dwordx2 v[44:45], v[34:35], off offset:32
	v_mul_f32_e32 v34, 0xbfb8aa3b, v30
	v_mul_f32_e32 v35, 0xbfb8aa3b, v31
; DI float sigmoidf_(float v) { return __builtin_amdgcn_rcpf(1.f + __expf(-v)); }
; #define WAIT_V(n) asm volatile("s_waitcnt vmcnt(" #n ")" ::: "memory")
; #define BAR __builtin_amdgcn_s_barrier()
; #define EPI_SCHED __builtin_amdgcn_sched_barrier(0)
; template <class EPI>
; DI void gemm_stream(const u16* __restrict__ A, const u16* __restrict__ Bt, const int K, const int nM, const int nN,
;                     const int bid, const int nb, const int tid, EPI epi) {
;     ...
;   WAIT_V(0);
;   if (wr == 0) BAR;
;   BAR;
; DI void gemm_gateup(const Params& p, int bid, int nb, int tid) {
;     ...
;     _Pragma("unroll") for (int ai = 0; ai < 2; ++ai) _Pragma("unroll") for (int m = 0; m < 4; ++m) _Pragma("unroll") for (int n = 0; n < 2; ++n) {
;       const int col = pn * 128 + wc * 32 + n * 16 + fq * 4;
;       const int row = brow + ai * HALF + wr * 64 + m * 16 + fr;
;       const f32x4 g = acc[ai][0][m][n], uu = acc[ai][1][m][n];
;       uint2 w;
;       w.x = pk2(g[0] * sigmoidf_(g[0]) * uu[0], g[1] * sigmoidf_(g[1]) * uu[1]);
;       w.y = pk2(g[2] * sigmoidf_(g[2]) * uu[2], g[3] * sigmoidf_(g[3]) * uu[3]);
;       *reinterpret_cast<uint2*>(C + (size_t)row * DFF + col) = w;
;       EPI_SCHED;
;     }
	v_exp_f32_e32 v34, v34
	v_exp_f32_e32 v35, v35
	v_add_u32_e32 v36, 0xa0, v148
	v_add_f32_e32 v34, 1.0, v34
	v_add_f32_e32 v35, 1.0, v35
	v_rcp_f32_e32 v34, v34
	v_rcp_f32_e32 v35, v35
	s_nop 0
	v_pk_mul_f32 v[30:31], v[30:31], v[34:35]
	s_nop 0
	v_pk_mul_f32 v[26:27], v[30:31], v[26:27]
	s_nop 0
	v_cvt_pk_bf16_f32 v26, v26, v27
	v_mul_f32_e32 v27, 0xbfb8aa3b, v32
	v_exp_f32_e32 v27, v27
	s_nop 0
	v_add_f32_e32 v27, 1.0, v27
	v_rcp_f32_e32 v30, v27
	v_mul_f32_e32 v27, 0xbfb8aa3b, v33
	v_exp_f32_e32 v27, v27
	s_nop 0
	v_add_f32_e32 v27, 1.0, v27
	v_rcp_f32_e32 v31, v27
	s_nop 0
	v_pk_mul_f32 v[30:31], v[32:33], v[30:31]
	s_nop 0
	v_pk_mul_f32 v[28:29], v[30:31], v[28:29]
	s_nop 0
	v_cvt_pk_bf16_f32 v27, v28, v29
	v_mad_i64_i32 v[28:29], s[8:9], v36, s7, v[122:123]
	v_lshl_add_u64 v[28:29], v[28:29], 0, v[124:125]
	global_store_dwordx2 v[28:29], v[26:27], off
	v_mul_f32_e32 v26, 0xbfb8aa3b, v22
	v_mul_f32_e32 v27, 0xbfb8aa3b, v23
	v_exp_f32_e32 v26, v26
	v_exp_f32_e32 v27, v27
	v_add_f32_e32 v26, 1.0, v26
	v_add_f32_e32 v27, 1.0, v27
	v_rcp_f32_e32 v26, v26
	v_rcp_f32_e32 v27, v27
	s_nop 0
	v_pk_mul_f32 v[22:23], v[22:23], v[26:27]
	s_nop 0
	v_pk_mul_f32 v[18:19], v[22:23], v[18:19]
	s_nop 0
	v_cvt_pk_bf16_f32 v18, v18, v19
	v_mul_f32_e32 v19, 0xbfb8aa3b, v24
	v_exp_f32_e32 v19, v19
	s_nop 0
	v_add_f32_e32 v19, 1.0, v19
	v_rcp_f32_e32 v22, v19
	v_mul_f32_e32 v19, 0xbfb8aa3b, v25
	v_exp_f32_e32 v19, v19
	s_nop 0
	v_add_f32_e32 v19, 1.0, v19
	v_rcp_f32_e32 v23, v19
	s_nop 0
	v_pk_mul_f32 v[22:23], v[24:25], v[22:23]
	s_nop 0
	v_pk_mul_f32 v[20:21], v[22:23], v[20:21]
	s_nop 0
	v_cvt_pk_bf16_f32 v19, v20, v21
	global_store_dwordx2 v[28:29], v[18:19], off offset:32
	v_mul_f32_e32 v18, 0xbfb8aa3b, v14
	v_mul_f32_e32 v19, 0xbfb8aa3b, v15
	v_exp_f32_e32 v18, v18
	v_exp_f32_e32 v19, v19
	v_add_u32_e32 v20, 0xb0, v148
	v_add_f32_e32 v18, 1.0, v18
	v_add_f32_e32 v19, 1.0, v19
	v_rcp_f32_e32 v18, v18
	v_rcp_f32_e32 v19, v19
	s_nop 0
	v_pk_mul_f32 v[14:15], v[14:15], v[18:19]
	s_nop 0
	v_pk_mul_f32 v[10:11], v[14:15], v[10:11]
	s_nop 0
	v_cvt_pk_bf16_f32 v10, v10, v11
	v_mul_f32_e32 v11, 0xbfb8aa3b, v16
	v_exp_f32_e32 v11, v11
	s_nop 0
	v_add_f32_e32 v11, 1.0, v11
	v_rcp_f32_e32 v14, v11
	v_mul_f32_e32 v11, 0xbfb8aa3b, v17
	v_exp_f32_e32 v11, v11
	s_nop 0
	v_add_f32_e32 v11, 1.0, v11
	v_rcp_f32_e32 v15, v11
	s_nop 0
	v_pk_mul_f32 v[14:15], v[16:17], v[14:15]
	s_nop 0
	v_pk_mul_f32 v[12:13], v[14:15], v[12:13]
	s_nop 0
	v_cvt_pk_bf16_f32 v11, v12, v13
	v_mad_i64_i32 v[12:13], s[8:9], v20, s7, v[122:123]
	v_lshl_add_u64 v[12:13], v[12:13], 0, v[124:125]
	global_store_dwordx2 v[12:13], v[10:11], off
	v_mul_f32_e32 v10, 0xbfb8aa3b, v6
	v_mul_f32_e32 v11, 0xbfb8aa3b, v7
	v_exp_f32_e32 v10, v10
	v_exp_f32_e32 v11, v11
	v_add_f32_e32 v10, 1.0, v10
	v_add_f32_e32 v11, 1.0, v11
	v_rcp_f32_e32 v10, v10
	v_rcp_f32_e32 v11, v11
	s_nop 0
	v_pk_mul_f32 v[6:7], v[6:7], v[10:11]
	s_nop 0
	v_pk_mul_f32 v[2:3], v[6:7], v[2:3]
	s_nop 0
	v_cvt_pk_bf16_f32 v2, v2, v3
	v_mul_f32_e32 v3, 0xbfb8aa3b, v8
	v_exp_f32_e32 v3, v3
	s_nop 0
	v_add_f32_e32 v3, 1.0, v3
	v_rcp_f32_e32 v6, v3
	v_mul_f32_e32 v3, 0xbfb8aa3b, v9
	v_exp_f32_e32 v3, v3
	s_nop 0
	v_add_f32_e32 v3, 1.0, v3
	v_rcp_f32_e32 v7, v3
	s_nop 0
	v_pk_mul_f32 v[6:7], v[8:9], v[6:7]
	s_nop 0
	v_pk_mul_f32 v[4:5], v[6:7], v[4:5]
	s_nop 0
	v_cvt_pk_bf16_f32 v3, v4, v5
	global_store_dwordx2 v[12:13], v[2:3], off offset:32
	s_and_b64 vcc, exec, s[0:1]
	s_mov_b32 s8, s5
	s_mov_b32 s9, s6
	s_mov_b32 s7, s4
	s_cbranch_vccz .LBB0_43
	s_waitcnt vmcnt(0)
	s_movk_i32 s0, 0x100
	v_cmp_gt_u32_e32 vcc, s0, v239
	s_and_saveexec_b64 s[0:1], vcc
	s_cbranch_execz .LBB0_50
	s_barrier

.LBB0_132:
	v_or_b32_e32 v131, 0x10000, v167
	v_add_u32_e32 v136, 0x10400, v167
	v_add_u32_e32 v140, 0x10800, v167
	v_add_u32_e32 v144, 0x10c00, v167
	s_add_i32 s11, s10, 2
	ds_read_b128 v[132:135], v131
	ds_read_b128 v[136:139], v136
	ds_read_b128 v[140:143], v140
	ds_read_b128 v[144:147], v144
	s_cmp_lt_u32 s10, 30
	s_cselect_b32 s12, s8, s5
	s_cselect_b32 s13, s7, s6
	s_cselect_b32 s14, s9, 0
	s_lshl_b32 s13, s13, 11
	s_lshl_b32 s12, s12, 11
	s_or_b32 s15, s14, 64
	s_add_i32 s17, s12, s14
	s_or_b32 s18, s13, 0x40000
	s_add_i32 s16, s13, s14
	s_add_i32 s13, s15, s13
	s_add_i32 s12, s15, s12
	s_lshl_b32 s17, s17, 1
	s_add_i32 s19, s18, s14
	s_add_i32 s18, s18, s15
	s_addk_i32 s9, 0x80
	s_lshl_b32 s16, s16, 1
	s_lshl_b32 s14, s13, 1
	s_lshl_b32 s13, s12, 1
	s_lshl_b32 s15, s19, 1
	s_add_i32 s19, s17, 0x80000
	s_lshl_b32 s12, s18, 1
	s_cmp_gt_u32 s10, 29
	v_add_u32_e32 v148, 0xc000, v0
	v_add_u32_e32 v131, 0xfffc0000, v130
	v_readfirstlane_b32 s10, v148
	s_mov_b32 m0, s10
	ds_read_b128 v[170:173], v166
	ds_read_b128 v[174:177], v166 offset:1024
	ds_read_b128 v[180:183], v166 offset:2048
	ds_read_b128 v[184:187], v166 offset:3072
	ds_read_b128 v[188:191], v166 offset:4096
	ds_read_b128 v[192:195], v166 offset:5120
	ds_read_b128 v[196:199], v166 offset:6144
	ds_read_b128 v[200:203], v166 offset:7168
	global_load_lds_dwordx4 v131, s[86:87]
	v_add_u32_e32 v131, 0xe000, v0
	s_nop 0
	s_bitset1_b32 m0, 13
	s_nop 0
	global_load_lds_dwordx4 v130, s[86:87]
	s_waitcnt lgkmcnt(8)
	v_or_b32_e32 v131, 0x14000, v167
	v_add_u32_e32 v148, 0x14400, v167
	ds_read_b128 v[204:207], v131
	ds_read_b128 v[208:211], v148
	v_add_u32_e32 v131, 0x14800, v167
	v_add_u32_e32 v148, 0x14c00, v167
	ds_read_b128 v[212:215], v131
	ds_read_b128 v[216:219], v148
	s_waitcnt vmcnt(8)
	s_waitcnt lgkmcnt(0)
	s_barrier
	s_setprio 1
	v_mfma_f32_16x16x32_bf16 v[98:101], v[132:135], v[170:173], v[98:101]
	v_mfma_f32_16x16x32_bf16 v[102:105], v[140:143], v[170:173], v[102:105]
	v_mfma_f32_16x16x32_bf16 v[126:129], v[132:135], v[180:183], v[126:129]
	v_mfma_f32_16x16x32_bf16 v[122:125], v[140:143], v[180:183], v[122:125]
	v_mfma_f32_16x16x32_bf16 v[118:121], v[132:135], v[188:191], v[118:121]
	v_mfma_f32_16x16x32_bf16 v[114:117], v[140:143], v[188:191], v[114:117]
	v_mfma_f32_16x16x32_bf16 v[110:113], v[132:135], v[196:199], v[110:113]
	v_mfma_f32_16x16x32_bf16 v[106:109], v[140:143], v[196:199], v[106:109]
	v_mfma_f32_16x16x32_bf16 v[98:101], v[136:139], v[174:177], v[98:101]
	v_mfma_f32_16x16x32_bf16 v[102:105], v[144:147], v[174:177], v[102:105]
	v_mfma_f32_16x16x32_bf16 v[126:129], v[136:139], v[184:187], v[126:129]
	v_mfma_f32_16x16x32_bf16 v[122:125], v[144:147], v[184:187], v[122:125]
	v_mfma_f32_16x16x32_bf16 v[118:121], v[136:139], v[192:195], v[118:121]
	v_mfma_f32_16x16x32_bf16 v[114:117], v[144:147], v[192:195], v[114:117]
	v_mfma_f32_16x16x32_bf16 v[110:113], v[136:139], v[200:203], v[110:113]
	v_mfma_f32_16x16x32_bf16 v[106:109], v[144:147], v[200:203], v[106:109]
	v_mfma_f32_16x16x32_bf16 v[66:69], v[204:207], v[170:173], v[66:69]
	v_mfma_f32_16x16x32_bf16 v[70:73], v[212:215], v[170:173], v[70:73]
	v_mfma_f32_16x16x32_bf16 v[74:77], v[204:207], v[180:183], v[74:77]
	v_mfma_f32_16x16x32_bf16 v[78:81], v[212:215], v[180:183], v[78:81]
	v_mfma_f32_16x16x32_bf16 v[82:85], v[204:207], v[188:191], v[82:85]
	v_mfma_f32_16x16x32_bf16 v[86:89], v[212:215], v[188:191], v[86:89]
	v_mfma_f32_16x16x32_bf16 v[90:93], v[204:207], v[196:199], v[90:93]
	v_mfma_f32_16x16x32_bf16 v[94:97], v[212:215], v[196:199], v[94:97]
	v_mfma_f32_16x16x32_bf16 v[66:69], v[208:211], v[174:177], v[66:69]
	v_mfma_f32_16x16x32_bf16 v[70:73], v[216:219], v[174:177], v[70:73]
	v_mfma_f32_16x16x32_bf16 v[74:77], v[208:211], v[184:187], v[74:77]
	v_mfma_f32_16x16x32_bf16 v[78:81], v[216:219], v[184:187], v[78:81]
	v_mfma_f32_16x16x32_bf16 v[82:85], v[208:211], v[192:195], v[82:85]
	v_mfma_f32_16x16x32_bf16 v[86:89], v[216:219], v[192:195], v[86:89]
	v_mfma_f32_16x16x32_bf16 v[90:93], v[208:211], v[200:203], v[90:93]
	v_mfma_f32_16x16x32_bf16 v[94:97], v[216:219], v[200:203], v[94:97]
	s_setprio 0
	s_barrier
	v_readfirstlane_b32 s10, v152
	v_add_u32_e32 v131, s16, v150
	s_mov_b32 m0, s10
	global_load_lds_dwordx4 v131, s[88:89]
	v_add_u32_e32 v131, s16, v151
	s_bitset1_b32 m0, 13
	s_nop 0
	global_load_lds_dwordx4 v131, s[88:89]
	v_readfirstlane_b32 s10, v0
	v_add_u32_e32 v131, s17, v150
	s_mov_b32 m0, s10
	ds_read_b128 v[170:173], v166 offset:16384
	ds_read_b128 v[174:177], v166 offset:17408
	ds_read_b128 v[180:183], v166 offset:18432
	ds_read_b128 v[184:187], v166 offset:19456
	ds_read_b128 v[188:191], v166 offset:20480
	ds_read_b128 v[192:195], v166 offset:21504
	ds_read_b128 v[196:199], v166 offset:22528
	ds_read_b128 v[200:203], v166 offset:23552
	global_load_lds_dwordx4 v131, s[86:87]
	v_add_u32_e32 v131, s17, v151
	s_bitset1_b32 m0, 13
	s_nop 0
	global_load_lds_dwordx4 v131, s[86:87]
	v_readfirstlane_b32 s10, v155
	v_add_u32_e32 v131, s15, v150
	s_mov_b32 m0, s10
	global_load_lds_dwordx4 v131, s[88:89]
	v_add_u32_e32 v131, s15, v151
	s_bitset1_b32 m0, 13
	s_nop 0
	global_load_lds_dwordx4 v131, s[88:89]
	s_waitcnt vmcnt(8)
	s_waitcnt lgkmcnt(0)
	s_barrier
	s_setprio 1
	v_mfma_f32_16x16x32_bf16 v[34:37], v[132:135], v[170:173], v[34:37]
	v_mfma_f32_16x16x32_bf16 v[38:41], v[140:143], v[170:173], v[38:41]
	v_mfma_f32_16x16x32_bf16 v[42:45], v[132:135], v[180:183], v[42:45]
	v_mfma_f32_16x16x32_bf16 v[46:49], v[140:143], v[180:183], v[46:49]
	v_mfma_f32_16x16x32_bf16 v[50:53], v[132:135], v[188:191], v[50:53]
	v_mfma_f32_16x16x32_bf16 v[54:57], v[140:143], v[188:191], v[54:57]
	v_mfma_f32_16x16x32_bf16 v[58:61], v[132:135], v[196:199], v[58:61]
	v_mfma_f32_16x16x32_bf16 v[62:65], v[140:143], v[196:199], v[62:65]
	v_mfma_f32_16x16x32_bf16 v[34:37], v[136:139], v[174:177], v[34:37]
	v_mfma_f32_16x16x32_bf16 v[38:41], v[144:147], v[174:177], v[38:41]
	v_mfma_f32_16x16x32_bf16 v[42:45], v[136:139], v[184:187], v[42:45]
	v_mfma_f32_16x16x32_bf16 v[46:49], v[144:147], v[184:187], v[46:49]
	v_mfma_f32_16x16x32_bf16 v[50:53], v[136:139], v[192:195], v[50:53]
	v_mfma_f32_16x16x32_bf16 v[54:57], v[144:147], v[192:195], v[54:57]
	v_mfma_f32_16x16x32_bf16 v[58:61], v[136:139], v[200:203], v[58:61]
	v_mfma_f32_16x16x32_bf16 v[62:65], v[144:147], v[200:203], v[62:65]
	v_mfma_f32_16x16x32_bf16 v[2:5], v[204:207], v[170:173], v[2:5]
	v_mfma_f32_16x16x32_bf16 v[6:9], v[212:215], v[170:173], v[6:9]
	v_mfma_f32_16x16x32_bf16 v[10:13], v[204:207], v[180:183], v[10:13]
	v_mfma_f32_16x16x32_bf16 v[14:17], v[212:215], v[180:183], v[14:17]
	v_mfma_f32_16x16x32_bf16 v[18:21], v[204:207], v[188:191], v[18:21]
	v_mfma_f32_16x16x32_bf16 v[22:25], v[212:215], v[188:191], v[22:25]
	v_mfma_f32_16x16x32_bf16 v[26:29], v[204:207], v[196:199], v[26:29]
	v_mfma_f32_16x16x32_bf16 v[30:33], v[212:215], v[196:199], v[30:33]
	v_mfma_f32_16x16x32_bf16 v[2:5], v[208:211], v[174:177], v[2:5]
	v_mfma_f32_16x16x32_bf16 v[6:9], v[216:219], v[174:177], v[6:9]
	v_mfma_f32_16x16x32_bf16 v[10:13], v[208:211], v[184:187], v[10:13]
	v_mfma_f32_16x16x32_bf16 v[14:17], v[216:219], v[184:187], v[14:17]
	v_mfma_f32_16x16x32_bf16 v[18:21], v[208:211], v[192:195], v[18:21]
	v_mfma_f32_16x16x32_bf16 v[22:25], v[216:219], v[192:195], v[22:25]
	v_mfma_f32_16x16x32_bf16 v[26:29], v[208:211], v[200:203], v[26:29]
	v_mfma_f32_16x16x32_bf16 v[30:33], v[216:219], v[200:203], v[30:33]
	s_setprio 0
	s_barrier
	v_or_b32_e32 v131, 0x18000, v167
	v_add_u32_e32 v136, 0x18400, v167
	ds_read_b128 v[132:135], v131
	ds_read_b128 v[136:139], v136
	v_add_u32_e32 v131, 0x18800, v167
	v_add_u32_e32 v144, 0x18c00, v167
	ds_read_b128 v[140:143], v131
	ds_read_b128 v[144:147], v144
	v_readfirstlane_b32 s10, v157
	v_add_u32_e32 v131, s19, v150
	s_mov_b32 m0, s10
	ds_read_b128 v[170:173], v166 offset:32768
	ds_read_b128 v[174:177], v166 offset:33792
	ds_read_b128 v[180:183], v166 offset:34816
	ds_read_b128 v[184:187], v166 offset:35840
	ds_read_b128 v[188:191], v166 offset:36864
	ds_read_b128 v[192:195], v166 offset:37888
	ds_read_b128 v[196:199], v166 offset:38912
	ds_read_b128 v[200:203], v166 offset:39936
	global_load_lds_dwordx4 v131, s[86:87]
	v_add_u32_e32 v131, s19, v151
	s_bitset1_b32 m0, 13
	s_nop 0
	global_load_lds_dwordx4 v131, s[86:87]
	s_waitcnt lgkmcnt(8)
	v_or_b32_e32 v131, 0x1c000, v167
	v_add_u32_e32 v148, 0x1c400, v167
	ds_read_b128 v[204:207], v131
	ds_read_b128 v[208:211], v148
	v_add_u32_e32 v131, 0x1c800, v167
	v_add_u32_e32 v148, 0x1cc00, v167
	ds_read_b128 v[212:215], v131
	ds_read_b128 v[216:219], v148
	s_waitcnt vmcnt(8)
	s_waitcnt lgkmcnt(0)
	s_barrier
	s_setprio 1
	v_mfma_f32_16x16x32_bf16 v[98:101], v[132:135], v[170:173], v[98:101]
	v_mfma_f32_16x16x32_bf16 v[102:105], v[140:143], v[170:173], v[102:105]
	v_mfma_f32_16x16x32_bf16 v[126:129], v[132:135], v[180:183], v[126:129]
	v_mfma_f32_16x16x32_bf16 v[122:125], v[140:143], v[180:183], v[122:125]
	v_mfma_f32_16x16x32_bf16 v[118:121], v[132:135], v[188:191], v[118:121]
	v_mfma_f32_16x16x32_bf16 v[114:117], v[140:143], v[188:191], v[114:117]
	v_mfma_f32_16x16x32_bf16 v[110:113], v[132:135], v[196:199], v[110:113]
	v_mfma_f32_16x16x32_bf16 v[106:109], v[140:143], v[196:199], v[106:109]
	v_mfma_f32_16x16x32_bf16 v[98:101], v[136:139], v[174:177], v[98:101]
	v_mfma_f32_16x16x32_bf16 v[102:105], v[144:147], v[174:177], v[102:105]
	v_mfma_f32_16x16x32_bf16 v[126:129], v[136:139], v[184:187], v[126:129]
	v_mfma_f32_16x16x32_bf16 v[122:125], v[144:147], v[184:187], v[122:125]
	v_mfma_f32_16x16x32_bf16 v[118:121], v[136:139], v[192:195], v[118:121]
	v_mfma_f32_16x16x32_bf16 v[114:117], v[144:147], v[192:195], v[114:117]
	v_mfma_f32_16x16x32_bf16 v[110:113], v[136:139], v[200:203], v[110:113]
	v_mfma_f32_16x16x32_bf16 v[106:109], v[144:147], v[200:203], v[106:109]
	v_mfma_f32_16x16x32_bf16 v[66:69], v[204:207], v[170:173], v[66:69]
	v_mfma_f32_16x16x32_bf16 v[70:73], v[212:215], v[170:173], v[70:73]
	v_mfma_f32_16x16x32_bf16 v[74:77], v[204:207], v[180:183], v[74:77]
	v_mfma_f32_16x16x32_bf16 v[78:81], v[212:215], v[180:183], v[78:81]
	v_mfma_f32_16x16x32_bf16 v[82:85], v[204:207], v[188:191], v[82:85]
	v_mfma_f32_16x16x32_bf16 v[86:89], v[212:215], v[188:191], v[86:89]
	v_mfma_f32_16x16x32_bf16 v[90:93], v[204:207], v[196:199], v[90:93]
	v_mfma_f32_16x16x32_bf16 v[94:97], v[212:215], v[196:199], v[94:97]
	v_mfma_f32_16x16x32_bf16 v[66:69], v[208:211], v[174:177], v[66:69]
	v_mfma_f32_16x16x32_bf16 v[70:73], v[216:219], v[174:177], v[70:73]
	v_mfma_f32_16x16x32_bf16 v[74:77], v[208:211], v[184:187], v[74:77]
	v_mfma_f32_16x16x32_bf16 v[78:81], v[216:219], v[184:187], v[78:81]
	v_mfma_f32_16x16x32_bf16 v[82:85], v[208:211], v[192:195], v[82:85]
	v_mfma_f32_16x16x32_bf16 v[86:89], v[216:219], v[192:195], v[86:89]
	v_mfma_f32_16x16x32_bf16 v[90:93], v[208:211], v[200:203], v[90:93]
	v_mfma_f32_16x16x32_bf16 v[94:97], v[216:219], v[200:203], v[94:97]
	s_setprio 0
	s_barrier
; DI void gemm_resid(const u16* A, const u16* Bt, int K, const float* xin, float* xout, int bid, int nb, int tid) {
;     ...
; #pragma unroll
;     for (int ai = 0; ai < 2; ++ai)
; #pragma unroll
;       for (int bj = 0; bj < 2; ++bj) {
;         float4 xi[4][2];
; #pragma unroll
;         for (int m = 0; m < 4; ++m)
; #pragma unroll
;           for (int n = 0; n < 2; ++n) xi[m][n] = *reinterpret_cast<const float4*>(xin + (size_t)ACC_ROW * 2048 + ACC_COL);
	v_readfirstlane_b32 s10, v159
	v_add_u32_e32 v131, s14, v150
	s_mov_b32 m0, s10
	global_load_lds_dwordx4 v131, s[88:89]
	v_add_u32_e32 v131, s14, v151
	s_bitset1_b32 m0, 13
	s_nop 0
	global_load_lds_dwordx4 v131, s[88:89]
	v_readfirstlane_b32 s10, v161
	v_add_u32_e32 v131, s13, v150
	s_mov_b32 m0, s10
	ds_read_b128 v[170:173], v166 offset:49152
	ds_read_b128 v[174:177], v166 offset:50176
	ds_read_b128 v[180:183], v166 offset:51200
	ds_read_b128 v[184:187], v166 offset:52224
	ds_read_b128 v[188:191], v166 offset:53248
	ds_read_b128 v[192:195], v166 offset:54272
	ds_read_b128 v[196:199], v166 offset:55296
	ds_read_b128 v[200:203], v166 offset:56320
	global_load_lds_dwordx4 v131, s[86:87]
	v_add_u32_e32 v131, s13, v151
	s_bitset1_b32 m0, 13
	s_nop 0
	global_load_lds_dwordx4 v131, s[86:87]
	v_readfirstlane_b32 s10, v163
	v_add_u32_e32 v131, s12, v150
	s_mov_b32 m0, s10
	global_load_lds_dwordx4 v131, s[88:89]
	v_add_u32_e32 v131, s12, v151
	s_bitset1_b32 m0, 13
	s_nop 0
	global_load_lds_dwordx4 v131, s[88:89]
	s_waitcnt vmcnt(8)
	s_waitcnt lgkmcnt(0)
	s_barrier
	s_setprio 1
	v_mfma_f32_16x16x32_bf16 v[34:37], v[132:135], v[170:173], v[34:37]
	v_mfma_f32_16x16x32_bf16 v[38:41], v[140:143], v[170:173], v[38:41]
	v_mfma_f32_16x16x32_bf16 v[42:45], v[132:135], v[180:183], v[42:45]
	v_mfma_f32_16x16x32_bf16 v[46:49], v[140:143], v[180:183], v[46:49]
	v_mfma_f32_16x16x32_bf16 v[50:53], v[132:135], v[188:191], v[50:53]
	v_mfma_f32_16x16x32_bf16 v[54:57], v[140:143], v[188:191], v[54:57]
	v_mfma_f32_16x16x32_bf16 v[58:61], v[132:135], v[196:199], v[58:61]
	v_mfma_f32_16x16x32_bf16 v[62:65], v[140:143], v[196:199], v[62:65]
	v_mfma_f32_16x16x32_bf16 v[34:37], v[136:139], v[174:177], v[34:37]
	v_mfma_f32_16x16x32_bf16 v[38:41], v[144:147], v[174:177], v[38:41]
	v_mfma_f32_16x16x32_bf16 v[42:45], v[136:139], v[184:187], v[42:45]
	v_mfma_f32_16x16x32_bf16 v[46:49], v[144:147], v[184:187], v[46:49]
	v_mfma_f32_16x16x32_bf16 v[50:53], v[136:139], v[192:195], v[50:53]
	v_mfma_f32_16x16x32_bf16 v[54:57], v[144:147], v[192:195], v[54:57]
	v_mfma_f32_16x16x32_bf16 v[58:61], v[136:139], v[200:203], v[58:61]
	v_mfma_f32_16x16x32_bf16 v[62:65], v[144:147], v[200:203], v[62:65]
	v_mfma_f32_16x16x32_bf16 v[2:5], v[204:207], v[170:173], v[2:5]
	v_mfma_f32_16x16x32_bf16 v[6:9], v[212:215], v[170:173], v[6:9]
	v_mfma_f32_16x16x32_bf16 v[10:13], v[204:207], v[180:183], v[10:13]
	v_mfma_f32_16x16x32_bf16 v[14:17], v[212:215], v[180:183], v[14:17]
	v_mfma_f32_16x16x32_bf16 v[18:21], v[204:207], v[188:191], v[18:21]
	v_mfma_f32_16x16x32_bf16 v[22:25], v[212:215], v[188:191], v[22:25]
	v_mfma_f32_16x16x32_bf16 v[26:29], v[204:207], v[196:199], v[26:29]
	v_mfma_f32_16x16x32_bf16 v[30:33], v[212:215], v[196:199], v[30:33]
	v_mfma_f32_16x16x32_bf16 v[2:5], v[208:211], v[174:177], v[2:5]
	v_mfma_f32_16x16x32_bf16 v[6:9], v[216:219], v[174:177], v[6:9]
	v_mfma_f32_16x16x32_bf16 v[10:13], v[208:211], v[184:187], v[10:13]
	v_mfma_f32_16x16x32_bf16 v[14:17], v[216:219], v[184:187], v[14:17]
	v_mfma_f32_16x16x32_bf16 v[18:21], v[208:211], v[192:195], v[18:21]
	v_mfma_f32_16x16x32_bf16 v[22:25], v[216:219], v[192:195], v[22:25]
	v_mfma_f32_16x16x32_bf16 v[26:29], v[208:211], v[200:203], v[26:29]
	v_mfma_f32_16x16x32_bf16 v[30:33], v[216:219], v[200:203], v[30:33]
	s_setprio 0
	v_add_u32_e32 v130, 0x100, v130
	s_mov_b32 s10, s11
	s_barrier
	s_cbranch_scc0 .LBB0_132
	v_mov_b32_e32 v131, v239
	s_nop 0
	v_ashrrev_i32_e32 v130, 2, v131
	v_and_b32_e32 v130, 0xffffffc0, v130
	v_and_or_b32 v132, v131, 15, s8
	v_add_u32_e32 v130, v132, v130
	v_lshrrev_b32_e32 v132, 1, v131
	v_lshrrev_b32_e32 v131, 2, v131
	v_and_b32_e32 v132, 0x60, v132
	v_and_b32_e32 v131, 12, v131
	v_or3_b32 v132, v132, v131, s7
	v_ashrrev_i32_e32 v131, 31, v130
	v_ashrrev_i32_e32 v133, 31, v132
	v_lshlrev_b64 v[134:135], 13, v[130:131]
	v_lshl_add_u64 v[136:137], s[48:49], 0, v[134:135]
	v_lshlrev_b64 v[132:133], 2, v[132:133]
	v_lshl_add_u64 v[142:143], v[136:137], 0, v[132:133]
	v_or_b32_e32 v136, 16, v130
	v_ashrrev_i32_e32 v137, 31, v136
	v_lshlrev_b64 v[136:137], 13, v[136:137]
	v_lshl_add_u64 v[138:139], s[48:49], 0, v[136:137]
	v_lshl_add_u64 v[144:145], v[138:139], 0, v[132:133]
	v_or_b32_e32 v138, 32, v130
	v_ashrrev_i32_e32 v139, 31, v138
	v_lshlrev_b64 v[170:171], 13, v[138:139]
	v_lshl_add_u64 v[138:139], s[48:49], 0, v[170:171]
	v_lshl_add_u64 v[146:147], v[138:139], 0, v[132:133]
	v_or_b32_e32 v138, 48, v130
	v_ashrrev_i32_e32 v139, 31, v138
	v_lshlrev_b64 v[172:173], 13, v[138:139]
	v_lshl_add_u64 v[134:135], s[72:73], 0, v[134:135]
	v_lshl_add_u64 v[138:139], s[48:49], 0, v[172:173]
	v_lshl_add_u64 v[140:141], v[134:135], 0, v[132:133]
	v_lshl_add_u64 v[134:135], s[72:73], 0, v[136:137]
	v_lshl_add_u64 v[148:149], v[138:139], 0, v[132:133]
	v_lshl_add_u64 v[138:139], v[134:135], 0, v[132:133]
	v_lshl_add_u64 v[134:135], s[72:73], 0, v[170:171]
	v_lshl_add_u64 v[136:137], v[134:135], 0, v[132:133]
	v_lshl_add_u64 v[134:135], s[72:73], 0, v[172:173]
	v_lshl_add_u64 v[134:135], v[134:135], 0, v[132:133]
	global_load_dwordx4 v[180:183], v[148:149], off offset:64
	global_load_dwordx4 v[184:187], v[148:149], off
	global_load_dwordx4 v[188:191], v[146:147], off offset:64
	global_load_dwordx4 v[192:195], v[146:147], off
	global_load_dwordx4 v[196:199], v[144:145], off offset:64
	global_load_dwordx4 v[200:203], v[144:145], off
	global_load_dwordx4 v[204:207], v[142:143], off offset:64
	global_load_dwordx4 v[208:211], v[142:143], off
	s_waitcnt vmcnt(0)
; #define EPI_SCHED __builtin_amdgcn_sched_barrier(0)
; DI void gemm_resid(const u16* A, const u16* Bt, int K, const float* xin, float* xout, int bid, int nb, int tid) {
;     ...
; #pragma unroll
;     for (int ai = 0; ai < 2; ++ai)
; #pragma unroll
;       for (int bj = 0; bj < 2; ++bj) {
;         float4 xi[4][2];
; #pragma unroll
;         for (int m = 0; m < 4; ++m)
; #pragma unroll
;           for (int n = 0; n < 2; ++n) xi[m][n] = *reinterpret_cast<const float4*>(xin + (size_t)ACC_ROW * 2048 + ACC_COL);
; #pragma unroll
;         for (int m = 0; m < 4; ++m)
; #pragma unroll
;           for (int n = 0; n < 2; ++n) {
;             const f32x4 v = acc[ai][bj][m][n];
;             float4 r; r.x = xi[m][n].x + v[0]; r.y = xi[m][n].y + v[1]; r.z = xi[m][n].z + v[2]; r.w = xi[m][n].w + v[3];
;             *reinterpret_cast<float4*>(xout + (size_t)ACC_ROW * 2048 + ACC_COL) = r;
;           }
;         EPI_SCHED;
;       }
	v_pk_add_f32 v[106:107], v[106:107], v[180:181]
	v_pk_add_f32 v[108:109], v[108:109], v[182:183]
	v_pk_add_f32 v[110:111], v[110:111], v[184:185]
	v_pk_add_f32 v[112:113], v[112:113], v[186:187]
	v_pk_add_f32 v[114:115], v[114:115], v[188:189]
	v_pk_add_f32 v[116:117], v[116:117], v[190:191]
	v_pk_add_f32 v[118:119], v[118:119], v[192:193]
	v_pk_add_f32 v[120:121], v[120:121], v[194:195]
	v_pk_add_f32 v[122:123], v[122:123], v[196:197]
	v_pk_add_f32 v[124:125], v[124:125], v[198:199]
	v_pk_add_f32 v[126:127], v[126:127], v[200:201]
	v_pk_add_f32 v[128:129], v[128:129], v[202:203]
	v_pk_add_f32 v[102:103], v[102:103], v[204:205]
	v_pk_add_f32 v[104:105], v[104:105], v[206:207]
	v_pk_add_f32 v[98:99], v[98:99], v[208:209]
	v_pk_add_f32 v[100:101], v[100:101], v[210:211]
	global_store_dwordx4 v[140:141], v[98:101], off
	global_store_dwordx4 v[140:141], v[102:105], off offset:64
	global_store_dwordx4 v[138:139], v[126:129], off
	global_store_dwordx4 v[138:139], v[122:125], off offset:64
	global_store_dwordx4 v[136:137], v[118:121], off
	global_store_dwordx4 v[136:137], v[114:117], off offset:64
	global_store_dwordx4 v[134:135], v[110:113], off
	global_store_dwordx4 v[134:135], v[106:109], off offset:64
	global_load_dwordx4 v[180:183], v[148:149], off offset:576
	global_load_dwordx4 v[184:187], v[148:149], off offset:512
	global_load_dwordx4 v[188:191], v[146:147], off offset:576
	global_load_dwordx4 v[192:195], v[146:147], off offset:512
	global_load_dwordx4 v[196:199], v[144:145], off offset:576
	global_load_dwordx4 v[200:203], v[144:145], off offset:512
	global_load_dwordx4 v[204:207], v[142:143], off offset:576
	global_load_dwordx4 v[208:211], v[142:143], off offset:512
	s_waitcnt vmcnt(0)
	v_pk_add_f32 v[94:95], v[94:95], v[180:181]
	v_pk_add_f32 v[96:97], v[96:97], v[182:183]
	v_pk_add_f32 v[90:91], v[90:91], v[184:185]
	v_pk_add_f32 v[92:93], v[92:93], v[186:187]
	v_pk_add_f32 v[86:87], v[86:87], v[188:189]
	v_pk_add_f32 v[88:89], v[88:89], v[190:191]
	v_pk_add_f32 v[82:83], v[82:83], v[192:193]
	v_pk_add_f32 v[84:85], v[84:85], v[194:195]
	v_pk_add_f32 v[78:79], v[78:79], v[196:197]
	v_pk_add_f32 v[80:81], v[80:81], v[198:199]
	v_pk_add_f32 v[74:75], v[74:75], v[200:201]
	v_pk_add_f32 v[76:77], v[76:77], v[202:203]
	v_pk_add_f32 v[70:71], v[70:71], v[204:205]
	v_pk_add_f32 v[72:73], v[72:73], v[206:207]
	v_pk_add_f32 v[66:67], v[66:67], v[208:209]
	v_pk_add_f32 v[68:69], v[68:69], v[210:211]
	global_store_dwordx4 v[140:141], v[66:69], off offset:512
	global_store_dwordx4 v[140:141], v[70:73], off offset:576
	global_store_dwordx4 v[138:139], v[74:77], off offset:512
	global_store_dwordx4 v[138:139], v[78:81], off offset:576
	global_store_dwordx4 v[136:137], v[82:85], off offset:512
	global_store_dwordx4 v[136:137], v[86:89], off offset:576
	global_store_dwordx4 v[134:135], v[90:93], off offset:512
	global_store_dwordx4 v[134:135], v[94:97], off offset:576
	v_add_u32_e32 v66, 0x80, v130
	v_ashrrev_i32_e32 v67, 31, v66
	v_lshlrev_b64 v[66:67], 13, v[66:67]
	v_lshl_add_u64 v[68:69], s[48:49], 0, v[66:67]
	v_lshl_add_u64 v[74:75], v[68:69], 0, v[132:133]
	v_add_u32_e32 v68, 0x90, v130
	v_ashrrev_i32_e32 v69, 31, v68
	v_lshlrev_b64 v[68:69], 13, v[68:69]
	v_lshl_add_u64 v[70:71], s[48:49], 0, v[68:69]
	v_lshl_add_u64 v[76:77], v[70:71], 0, v[132:133]
	v_add_u32_e32 v70, 0xa0, v130
	v_ashrrev_i32_e32 v71, 31, v70
	v_lshlrev_b64 v[82:83], 13, v[70:71]
	v_lshl_add_u64 v[70:71], s[48:49], 0, v[82:83]
	v_lshl_add_u64 v[78:79], v[70:71], 0, v[132:133]
	v_add_u32_e32 v70, 0xb0, v130
	v_ashrrev_i32_e32 v71, 31, v70
	v_lshlrev_b64 v[84:85], 13, v[70:71]
	v_lshl_add_u64 v[66:67], s[72:73], 0, v[66:67]
	v_lshl_add_u64 v[70:71], s[48:49], 0, v[84:85]
	v_lshl_add_u64 v[72:73], v[66:67], 0, v[132:133]
	v_lshl_add_u64 v[66:67], s[72:73], 0, v[68:69]
	v_lshl_add_u64 v[80:81], v[70:71], 0, v[132:133]
	v_lshl_add_u64 v[70:71], v[66:67], 0, v[132:133]
	v_lshl_add_u64 v[66:67], s[72:73], 0, v[82:83]
	v_lshl_add_u64 v[68:69], v[66:67], 0, v[132:133]
	v_lshl_add_u64 v[66:67], s[72:73], 0, v[84:85]
	v_lshl_add_u64 v[66:67], v[66:67], 0, v[132:133]
	global_load_dwordx4 v[180:183], v[80:81], off offset:64
	global_load_dwordx4 v[184:187], v[80:81], off
	global_load_dwordx4 v[188:191], v[78:79], off offset:64
	global_load_dwordx4 v[192:195], v[78:79], off
	global_load_dwordx4 v[196:199], v[76:77], off offset:64
	global_load_dwordx4 v[200:203], v[76:77], off
	global_load_dwordx4 v[204:207], v[74:75], off offset:64
	global_load_dwordx4 v[208:211], v[74:75], off
	s_waitcnt vmcnt(0)
; #define WAIT_V(n) asm volatile("s_waitcnt vmcnt(" #n ")" ::: "memory")
; #define BAR __builtin_amdgcn_s_barrier()
; #define EPI_SCHED __builtin_amdgcn_sched_barrier(0)
; template <class EPI>
; DI void gemm_stream(const u16* __restrict__ A, const u16* __restrict__ Bt, const int K, const int nM, const int nN,
;                     const int bid, const int nb, const int tid, EPI epi) {
;     ...
;   WAIT_V(0);
;   if (wr == 0) BAR;
;   BAR;
; DI void gemm_resid(const u16* A, const u16* Bt, int K, const float* xin, float* xout, int bid, int nb, int tid) {
;     ...
; #pragma unroll
;     for (int ai = 0; ai < 2; ++ai)
; #pragma unroll
;       for (int bj = 0; bj < 2; ++bj) {
;         float4 xi[4][2];
; #pragma unroll
;         for (int m = 0; m < 4; ++m)
; #pragma unroll
;           for (int n = 0; n < 2; ++n) xi[m][n] = *reinterpret_cast<const float4*>(xin + (size_t)ACC_ROW * 2048 + ACC_COL);
; #pragma unroll
;         for (int m = 0; m < 4; ++m)
; #pragma unroll
;           for (int n = 0; n < 2; ++n) {
;             const f32x4 v = acc[ai][bj][m][n];
;             float4 r; r.x = xi[m][n].x + v[0]; r.y = xi[m][n].y + v[1]; r.z = xi[m][n].z + v[2]; r.w = xi[m][n].w + v[3];
;             *reinterpret_cast<float4*>(xout + (size_t)ACC_ROW * 2048 + ACC_COL) = r;
;           }
;         EPI_SCHED;
;       }
	v_pk_add_f32 v[62:63], v[62:63], v[180:181]
	v_pk_add_f32 v[64:65], v[64:65], v[182:183]
	v_pk_add_f32 v[58:59], v[58:59], v[184:185]
	v_pk_add_f32 v[60:61], v[60:61], v[186:187]
	v_pk_add_f32 v[54:55], v[54:55], v[188:189]
	v_pk_add_f32 v[56:57], v[56:57], v[190:191]
	v_pk_add_f32 v[50:51], v[50:51], v[192:193]
	v_pk_add_f32 v[52:53], v[52:53], v[194:195]
	v_pk_add_f32 v[46:47], v[46:47], v[196:197]
	v_pk_add_f32 v[48:49], v[48:49], v[198:199]
	v_pk_add_f32 v[42:43], v[42:43], v[200:201]
	v_pk_add_f32 v[44:45], v[44:45], v[202:203]
	v_pk_add_f32 v[38:39], v[38:39], v[204:205]
	v_pk_add_f32 v[40:41], v[40:41], v[206:207]
	v_pk_add_f32 v[34:35], v[34:35], v[208:209]
	v_pk_add_f32 v[36:37], v[36:37], v[210:211]
	global_store_dwordx4 v[72:73], v[34:37], off
	global_store_dwordx4 v[72:73], v[38:41], off offset:64
	global_store_dwordx4 v[70:71], v[42:45], off
	global_store_dwordx4 v[70:71], v[46:49], off offset:64
	global_store_dwordx4 v[68:69], v[50:53], off
	global_store_dwordx4 v[68:69], v[54:57], off offset:64
	global_store_dwordx4 v[66:67], v[58:61], off
	global_store_dwordx4 v[66:67], v[62:65], off offset:64
	global_load_dwordx4 v[180:183], v[80:81], off offset:576
	global_load_dwordx4 v[184:187], v[80:81], off offset:512
	global_load_dwordx4 v[188:191], v[78:79], off offset:576
	global_load_dwordx4 v[192:195], v[78:79], off offset:512
	global_load_dwordx4 v[196:199], v[76:77], off offset:576
	global_load_dwordx4 v[200:203], v[76:77], off offset:512
	global_load_dwordx4 v[204:207], v[74:75], off offset:576
	global_load_dwordx4 v[208:211], v[74:75], off offset:512
	s_waitcnt vmcnt(0)
	v_pk_add_f32 v[30:31], v[30:31], v[180:181]
	v_pk_add_f32 v[32:33], v[32:33], v[182:183]
	v_pk_add_f32 v[26:27], v[26:27], v[184:185]
	v_pk_add_f32 v[28:29], v[28:29], v[186:187]
	v_pk_add_f32 v[22:23], v[22:23], v[188:189]
	v_pk_add_f32 v[24:25], v[24:25], v[190:191]
	v_pk_add_f32 v[18:19], v[18:19], v[192:193]
	v_pk_add_f32 v[20:21], v[20:21], v[194:195]
	v_pk_add_f32 v[14:15], v[14:15], v[196:197]
	v_pk_add_f32 v[16:17], v[16:17], v[198:199]
	v_pk_add_f32 v[10:11], v[10:11], v[200:201]
	v_pk_add_f32 v[12:13], v[12:13], v[202:203]
	v_pk_add_f32 v[6:7], v[6:7], v[204:205]
	v_pk_add_f32 v[8:9], v[8:9], v[206:207]
	v_pk_add_f32 v[2:3], v[2:3], v[208:209]
	v_pk_add_f32 v[4:5], v[4:5], v[210:211]
	global_store_dwordx4 v[72:73], v[2:5], off offset:512
	global_store_dwordx4 v[72:73], v[6:9], off offset:576
	global_store_dwordx4 v[70:71], v[10:13], off offset:512
	global_store_dwordx4 v[70:71], v[14:17], off offset:576
	global_store_dwordx4 v[68:69], v[18:21], off offset:512
	global_store_dwordx4 v[68:69], v[22:25], off offset:576
	global_store_dwordx4 v[66:67], v[26:29], off offset:512
	global_store_dwordx4 v[66:67], v[30:33], off offset:576
	s_and_b64 vcc, exec, s[0:1]
	s_mov_b32 s8, s5
	s_mov_b32 s7, s6
	s_cbranch_vccz .LBB0_129
	s_waitcnt vmcnt(0)
	s_movk_i32 s0, 0x100
	v_cmp_gt_u32_e32 vcc, s0, v239
	s_and_saveexec_b64 s[0:1], vcc
	s_cbranch_execz .LBB0_136
	s_barrier

.Lpj48_loop:
	v_or_b32_e32 v122, 0x10000, v200
	v_add_u32_e32 v134, 0x10400, v200
	v_add_u32_e32 v138, 0x10800, v200
	v_add_u32_e32 v142, 0x10c00, v200
	ds_read_b128 v[122:125], v122
	ds_read_b128 v[134:137], v134
	ds_read_b128 v[138:141], v138
	ds_read_b128 v[142:145], v142
	s_add_i32 s1, s0, -2
	s_cmp_lt_u32 s1, 30
	s_cselect_b32 s3, s4, s16
	s_cselect_b32 s5, s2, s15
	v_add_u32_e32 v181, 0xc000, v179
	v_add_u32_e32 v180, 0xfffc0000, v0
	v_readfirstlane_b32 s6, v181
	s_mov_b32 m0, s6
	ds_read_b128 v[146:149], v199
	ds_read_b128 v[150:153], v199 offset:1024
	ds_read_b128 v[154:157], v199 offset:2048
	ds_read_b128 v[158:161], v199 offset:3072
	ds_read_b128 v[162:165], v199 offset:4096
	ds_read_b128 v[166:169], v199 offset:5120
	ds_read_b128 v[170:173], v199 offset:6144
	ds_read_b128 v[174:177], v199 offset:7168
	global_load_lds_dwordx4 v180, s[80:81]
	v_add_u32_e32 v180, 0xe000, v179
	s_nop 0
	s_bitset1_b32 m0, 13
	s_nop 0
	global_load_lds_dwordx4 v0, s[80:81]
	s_waitcnt lgkmcnt(8)
	v_or_b32_e32 v180, 0x14000, v200
	v_add_u32_e32 v202, 0x14400, v200
	v_add_u32_e32 v206, 0x14800, v200
	v_add_u32_e32 v210, 0x14c00, v200
	ds_read_b128 v[180:183], v180
	ds_read_b128 v[202:205], v202
	ds_read_b128 v[206:209], v206
	ds_read_b128 v[210:213], v210
	s_waitcnt vmcnt(8)
	s_waitcnt lgkmcnt(0)
	s_barrier
	s_setprio 1
	v_mfma_f32_16x16x32_bf16 v[130:133], v[122:125], v[146:149], v[130:133]
	v_mfma_f32_16x16x32_bf16 v[110:113], v[122:125], v[154:157], v[110:113]
	v_mfma_f32_16x16x32_bf16 v[94:97], v[122:125], v[162:165], v[94:97]
	v_mfma_f32_16x16x32_bf16 v[78:81], v[122:125], v[170:173], v[78:81]
	v_mfma_f32_16x16x32_bf16 v[130:133], v[134:137], v[150:153], v[130:133]
	v_mfma_f32_16x16x32_bf16 v[110:113], v[134:137], v[158:161], v[110:113]
	v_mfma_f32_16x16x32_bf16 v[94:97], v[134:137], v[166:169], v[94:97]
	v_mfma_f32_16x16x32_bf16 v[78:81], v[134:137], v[174:177], v[78:81]
	s_setprio 0
	s_barrier
	s_cselect_b32 s6, s0, 0
	s_lshl_b32 s3, s3, 11
	s_lshl_b32 s7, s6, 6
	s_or_b32 s10, s3, s7
	s_lshl_b32 s10, s10, 1
	v_readfirstlane_b32 s11, v186
	v_add_u32_e32 v214, s10, v184
	s_mov_b32 m0, s11
	global_load_lds_dwordx4 v214, s[74:75]
	v_add_u32_e32 v214, s10, v185
	s_bitset1_b32 m0, 13
	s_nop 0
	global_load_lds_dwordx4 v214, s[74:75]
	s_lshl_b32 s10, s5, 11
	s_or_b32 s11, s10, s7
	s_lshl_b32 s11, s11, 1
	v_readfirstlane_b32 s18, v179
	v_add_u32_e32 v214, s11, v184
	s_mov_b32 m0, s18
	ds_read_b128 v[146:149], v199 offset:16384
	ds_read_b128 v[150:153], v199 offset:17408
	ds_read_b128 v[154:157], v199 offset:18432
	ds_read_b128 v[158:161], v199 offset:19456
	ds_read_b128 v[162:165], v199 offset:20480
	ds_read_b128 v[166:169], v199 offset:21504
	ds_read_b128 v[170:173], v199 offset:22528
	ds_read_b128 v[174:177], v199 offset:23552
	global_load_lds_dwordx4 v214, s[80:81]
	v_add_u32_e32 v214, s11, v185
	s_bitset1_b32 m0, 13
	s_nop 0
	global_load_lds_dwordx4 v214, s[80:81]
	s_or_b32 s11, s3, 0x40000
	s_or_b32 s18, s11, s7
	s_lshl_b32 s18, s18, 1
	v_readfirstlane_b32 s19, v189
	v_add_u32_e32 v215, s18, v184
	s_mov_b32 m0, s19
	s_nop 0
	global_load_lds_dwordx4 v215, s[74:75]
	v_add_u32_e32 v215, s18, v185
	s_bitset1_b32 m0, 13
	s_nop 0
	global_load_lds_dwordx4 v215, s[74:75]
	s_waitcnt vmcnt(8)
	s_waitcnt lgkmcnt(0)
	s_barrier
	s_setprio 1
	v_mfma_f32_16x16x32_bf16 v[62:65], v[122:125], v[146:149], v[62:65]
	v_mfma_f32_16x16x32_bf16 v[46:49], v[122:125], v[154:157], v[46:49]
	v_mfma_f32_16x16x32_bf16 v[30:33], v[122:125], v[162:165], v[30:33]
	v_mfma_f32_16x16x32_bf16 v[14:17], v[122:125], v[170:173], v[14:17]
	v_mfma_f32_16x16x32_bf16 v[62:65], v[134:137], v[150:153], v[62:65]
	v_mfma_f32_16x16x32_bf16 v[46:49], v[134:137], v[158:161], v[46:49]
	v_mfma_f32_16x16x32_bf16 v[30:33], v[134:137], v[166:169], v[30:33]
	v_mfma_f32_16x16x32_bf16 v[14:17], v[134:137], v[174:177], v[14:17]
	s_setprio 0
	s_barrier
	v_or_b32_e32 v122, 0x18000, v200
	v_add_u32_e32 v134, 0x18400, v200
	v_add_u32_e32 v138, 0x18800, v200
	v_add_u32_e32 v142, 0x18c00, v200
	ds_read_b128 v[122:125], v122
	ds_read_b128 v[134:137], v134
	ds_read_b128 v[138:141], v138
	ds_read_b128 v[142:145], v142
	s_lshl_b32 s5, s5, 12
	s_lshl_b32 s6, s6, 7
	s_add_i32 s5, s6, s5
	s_add_i32 s5, s5, 0x80000
	v_readfirstlane_b32 s6, v191
	v_add_u32_e32 v180, s5, v184
	s_mov_b32 m0, s6
	ds_read_b128 v[146:149], v199 offset:32768
	ds_read_b128 v[150:153], v199 offset:33792
	ds_read_b128 v[154:157], v199 offset:34816
	ds_read_b128 v[158:161], v199 offset:35840
	ds_read_b128 v[162:165], v199 offset:36864
	ds_read_b128 v[166:169], v199 offset:37888
	ds_read_b128 v[170:173], v199 offset:38912
	ds_read_b128 v[174:177], v199 offset:39936
	global_load_lds_dwordx4 v180, s[80:81]
	v_add_u32_e32 v180, s5, v185
	s_bitset1_b32 m0, 13
	s_nop 0
	global_load_lds_dwordx4 v180, s[80:81]
	s_waitcnt lgkmcnt(8)
	v_or_b32_e32 v180, 0x1c000, v200
	v_add_u32_e32 v202, 0x1c400, v200
	v_add_u32_e32 v206, 0x1c800, v200
	v_add_u32_e32 v210, 0x1cc00, v200
	ds_read_b128 v[180:183], v180
	ds_read_b128 v[202:205], v202
	ds_read_b128 v[206:209], v206
	ds_read_b128 v[210:213], v210
	s_waitcnt vmcnt(8)
	s_waitcnt lgkmcnt(0)
	s_barrier
	s_setprio 1
	v_mfma_f32_16x16x32_bf16 v[130:133], v[122:125], v[146:149], v[130:133]
	v_mfma_f32_16x16x32_bf16 v[110:113], v[122:125], v[154:157], v[110:113]
	v_mfma_f32_16x16x32_bf16 v[94:97], v[122:125], v[162:165], v[94:97]
	v_mfma_f32_16x16x32_bf16 v[78:81], v[122:125], v[170:173], v[78:81]
	v_mfma_f32_16x16x32_bf16 v[130:133], v[134:137], v[150:153], v[130:133]
	v_mfma_f32_16x16x32_bf16 v[110:113], v[134:137], v[158:161], v[110:113]
	v_mfma_f32_16x16x32_bf16 v[94:97], v[134:137], v[166:169], v[94:97]
	v_mfma_f32_16x16x32_bf16 v[78:81], v[134:137], v[174:177], v[78:81]
	s_setprio 0
	s_barrier
	s_or_b32 s5, s7, 64
	s_or_b32 s3, s5, s3
	s_lshl_b32 s3, s3, 1
	v_readfirstlane_b32 s6, v193
	v_add_u32_e32 v214, s3, v184
	s_mov_b32 m0, s6
	global_load_lds_dwordx4 v214, s[74:75]
	v_add_u32_e32 v214, s3, v185
	s_bitset1_b32 m0, 13
	s_nop 0
	global_load_lds_dwordx4 v214, s[74:75]
	s_or_b32 s3, s5, s10
	s_lshl_b32 s3, s3, 1
	v_readfirstlane_b32 s6, v195
	v_add_u32_e32 v214, s3, v184
	s_mov_b32 m0, s6
	ds_read_b128 v[146:149], v199 offset:49152
	ds_read_b128 v[150:153], v199 offset:50176
	ds_read_b128 v[154:157], v199 offset:51200
	ds_read_b128 v[158:161], v199 offset:52224
	ds_read_b128 v[162:165], v199 offset:53248
	ds_read_b128 v[166:169], v199 offset:54272
	ds_read_b128 v[170:173], v199 offset:55296
	ds_read_b128 v[174:177], v199 offset:56320
	global_load_lds_dwordx4 v214, s[80:81]
	v_add_u32_e32 v214, s3, v185
	s_bitset1_b32 m0, 13
	s_nop 0
	global_load_lds_dwordx4 v214, s[80:81]
	s_or_b32 s3, s11, s5
	s_lshl_b32 s3, s3, 1
	v_readfirstlane_b32 s5, v197
	v_add_u32_e32 v215, s3, v184
	s_mov_b32 m0, s5
	s_nop 0
	global_load_lds_dwordx4 v215, s[74:75]
	v_add_u32_e32 v215, s3, v185
	s_bitset1_b32 m0, 13
	s_nop 0
	global_load_lds_dwordx4 v215, s[74:75]
	s_waitcnt vmcnt(8)
	s_waitcnt lgkmcnt(0)
	s_barrier
	s_setprio 1
	v_mfma_f32_16x16x32_bf16 v[62:65], v[122:125], v[146:149], v[62:65]
	v_mfma_f32_16x16x32_bf16 v[46:49], v[122:125], v[154:157], v[46:49]
	v_mfma_f32_16x16x32_bf16 v[30:33], v[122:125], v[162:165], v[30:33]
	v_mfma_f32_16x16x32_bf16 v[14:17], v[122:125], v[170:173], v[14:17]
	v_mfma_f32_16x16x32_bf16 v[62:65], v[134:137], v[150:153], v[62:65]
	v_mfma_f32_16x16x32_bf16 v[46:49], v[134:137], v[158:161], v[46:49]
	v_mfma_f32_16x16x32_bf16 v[30:33], v[134:137], v[166:169], v[30:33]
	v_mfma_f32_16x16x32_bf16 v[14:17], v[134:137], v[174:177], v[14:17]
	s_setprio 0
	s_add_i32 s0, s0, 2
	s_cmp_gt_u32 s1, 29
	v_add_u32_e32 v0, 0x100, v0
	s_barrier
	s_cbranch_scc0 .Lpj48_loop
	s_branch .Lpj48_done

; template <class EPI>
; DI void gemm_stream(const u16* __restrict__ A, const u16* __restrict__ Bt, const int K, const int nM, const int nN,
;                     const int bid, const int nb, const int tid, EPI epi) {
;     ...
;     for (int t = 0; t < nt; t += 2) {
;       const bool inside = (t + 2 < nt);
;       const int brs = inside ? brow : brow2, bcs = inside ? bcol : bcol2, t2 = inside ? t + 2 : 0;
.LBB0_414:
	v_or_b32_e32 v122, 0x10000, v200
	v_add_u32_e32 v134, 0x10400, v200
	v_add_u32_e32 v138, 0x10800, v200
	v_add_u32_e32 v142, 0x10c00, v200
	ds_read_b128 v[122:125], v122
	ds_read_b128 v[134:137], v134
	ds_read_b128 v[138:141], v138
	ds_read_b128 v[142:145], v142
	s_add_i32 s1, s0, -2
	s_cmp_lt_u32 s1, 30
	s_cselect_b32 s3, s4, s16
	s_cselect_b32 s5, s2, s15
	v_add_u32_e32 v181, 0xc000, v179
	v_add_u32_e32 v180, 0xfffc0000, v0
	v_readfirstlane_b32 s6, v181
	s_mov_b32 m0, s6
	ds_read_b128 v[146:149], v199
	ds_read_b128 v[150:153], v199 offset:1024
	ds_read_b128 v[154:157], v199 offset:2048
	ds_read_b128 v[158:161], v199 offset:3072
	ds_read_b128 v[162:165], v199 offset:4096
	ds_read_b128 v[166:169], v199 offset:5120
	ds_read_b128 v[170:173], v199 offset:6144
	ds_read_b128 v[174:177], v199 offset:7168
	global_load_lds_dwordx4 v180, s[80:81]
	v_add_u32_e32 v180, 0xe000, v179
	s_nop 0
	s_bitset1_b32 m0, 13
	s_nop 0
	global_load_lds_dwordx4 v0, s[80:81]
	s_waitcnt lgkmcnt(8)
	v_or_b32_e32 v180, 0x14000, v200
	v_add_u32_e32 v202, 0x14400, v200
	v_add_u32_e32 v206, 0x14800, v200
	v_add_u32_e32 v210, 0x14c00, v200
	ds_read_b128 v[180:183], v180
	ds_read_b128 v[202:205], v202
	ds_read_b128 v[206:209], v206
	ds_read_b128 v[210:213], v210
	s_waitcnt vmcnt(8)
	s_waitcnt lgkmcnt(0)
	s_barrier
	s_setprio 1
	v_mfma_f32_16x16x32_bf16 v[130:133], v[122:125], v[146:149], v[130:133]
	v_mfma_f32_16x16x32_bf16 v[126:129], v[138:141], v[146:149], v[126:129]
	v_mfma_f32_16x16x32_bf16 v[110:113], v[122:125], v[154:157], v[110:113]
	v_mfma_f32_16x16x32_bf16 v[106:109], v[138:141], v[154:157], v[106:109]
	v_mfma_f32_16x16x32_bf16 v[94:97], v[122:125], v[162:165], v[94:97]
	v_mfma_f32_16x16x32_bf16 v[90:93], v[138:141], v[162:165], v[90:93]
	v_mfma_f32_16x16x32_bf16 v[78:81], v[122:125], v[170:173], v[78:81]
	v_mfma_f32_16x16x32_bf16 v[74:77], v[138:141], v[170:173], v[74:77]
	v_mfma_f32_16x16x32_bf16 v[130:133], v[134:137], v[150:153], v[130:133]
	v_mfma_f32_16x16x32_bf16 v[126:129], v[142:145], v[150:153], v[126:129]
	v_mfma_f32_16x16x32_bf16 v[110:113], v[134:137], v[158:161], v[110:113]
	v_mfma_f32_16x16x32_bf16 v[106:109], v[142:145], v[158:161], v[106:109]
	v_mfma_f32_16x16x32_bf16 v[94:97], v[134:137], v[166:169], v[94:97]
	v_mfma_f32_16x16x32_bf16 v[90:93], v[142:145], v[166:169], v[90:93]
	v_mfma_f32_16x16x32_bf16 v[78:81], v[134:137], v[174:177], v[78:81]
	v_mfma_f32_16x16x32_bf16 v[74:77], v[142:145], v[174:177], v[74:77]
	v_mfma_f32_16x16x32_bf16 v[118:121], v[180:183], v[146:149], v[118:121]
	v_mfma_f32_16x16x32_bf16 v[114:117], v[206:209], v[146:149], v[114:117]
	v_mfma_f32_16x16x32_bf16 v[102:105], v[180:183], v[154:157], v[102:105]
	v_mfma_f32_16x16x32_bf16 v[98:101], v[206:209], v[154:157], v[98:101]
	v_mfma_f32_16x16x32_bf16 v[86:89], v[180:183], v[162:165], v[86:89]
	v_mfma_f32_16x16x32_bf16 v[82:85], v[206:209], v[162:165], v[82:85]
	v_mfma_f32_16x16x32_bf16 v[70:73], v[180:183], v[170:173], v[70:73]
	v_mfma_f32_16x16x32_bf16 v[66:69], v[206:209], v[170:173], v[66:69]
	v_mfma_f32_16x16x32_bf16 v[118:121], v[202:205], v[150:153], v[118:121]
	v_mfma_f32_16x16x32_bf16 v[114:117], v[210:213], v[150:153], v[114:117]
	v_mfma_f32_16x16x32_bf16 v[102:105], v[202:205], v[158:161], v[102:105]
	v_mfma_f32_16x16x32_bf16 v[98:101], v[210:213], v[158:161], v[98:101]
	v_mfma_f32_16x16x32_bf16 v[86:89], v[202:205], v[166:169], v[86:89]
	v_mfma_f32_16x16x32_bf16 v[82:85], v[210:213], v[166:169], v[82:85]
	v_mfma_f32_16x16x32_bf16 v[70:73], v[202:205], v[174:177], v[70:73]
	v_mfma_f32_16x16x32_bf16 v[66:69], v[210:213], v[174:177], v[66:69]
	s_setprio 0
	s_barrier
	s_cselect_b32 s6, s0, 0
	s_lshl_b32 s3, s3, 11
	s_lshl_b32 s7, s6, 6
	s_or_b32 s10, s3, s7
	s_lshl_b32 s10, s10, 1
	v_readfirstlane_b32 s11, v186
	v_add_u32_e32 v214, s10, v184
	s_mov_b32 m0, s11
	global_load_lds_dwordx4 v214, s[74:75]
	v_add_u32_e32 v214, s10, v185
	s_bitset1_b32 m0, 13
	s_nop 0
	global_load_lds_dwordx4 v214, s[74:75]
	s_lshl_b32 s10, s5, 11
	s_or_b32 s11, s10, s7
	s_lshl_b32 s11, s11, 1
	v_readfirstlane_b32 s18, v179
	v_add_u32_e32 v214, s11, v184
	s_mov_b32 m0, s18
	ds_read_b128 v[146:149], v199 offset:16384
	ds_read_b128 v[150:153], v199 offset:17408
	ds_read_b128 v[154:157], v199 offset:18432
	ds_read_b128 v[158:161], v199 offset:19456
	ds_read_b128 v[162:165], v199 offset:20480
	ds_read_b128 v[166:169], v199 offset:21504
	ds_read_b128 v[170:173], v199 offset:22528
	ds_read_b128 v[174:177], v199 offset:23552
	global_load_lds_dwordx4 v214, s[80:81]
	v_add_u32_e32 v214, s11, v185
	s_bitset1_b32 m0, 13
	s_nop 0
	global_load_lds_dwordx4 v214, s[80:81]
	s_or_b32 s11, s3, 0x40000
	s_or_b32 s18, s11, s7
	s_lshl_b32 s18, s18, 1
	v_readfirstlane_b32 s19, v189
	v_add_u32_e32 v215, s18, v184
	s_mov_b32 m0, s19
	s_nop 0
	global_load_lds_dwordx4 v215, s[74:75]
	v_add_u32_e32 v215, s18, v185
	s_bitset1_b32 m0, 13
	s_nop 0
	global_load_lds_dwordx4 v215, s[74:75]
	s_waitcnt vmcnt(8)
	s_waitcnt lgkmcnt(0)
	s_barrier
	s_setprio 1
	v_mfma_f32_16x16x32_bf16 v[62:65], v[122:125], v[146:149], v[62:65]
	v_mfma_f32_16x16x32_bf16 v[58:61], v[138:141], v[146:149], v[58:61]
	v_mfma_f32_16x16x32_bf16 v[46:49], v[122:125], v[154:157], v[46:49]
	v_mfma_f32_16x16x32_bf16 v[42:45], v[138:141], v[154:157], v[42:45]
	v_mfma_f32_16x16x32_bf16 v[30:33], v[122:125], v[162:165], v[30:33]
	v_mfma_f32_16x16x32_bf16 v[26:29], v[138:141], v[162:165], v[26:29]
	v_mfma_f32_16x16x32_bf16 v[14:17], v[122:125], v[170:173], v[14:17]
	v_mfma_f32_16x16x32_bf16 v[10:13], v[138:141], v[170:173], v[10:13]
	v_mfma_f32_16x16x32_bf16 v[62:65], v[134:137], v[150:153], v[62:65]
	v_mfma_f32_16x16x32_bf16 v[58:61], v[142:145], v[150:153], v[58:61]
	v_mfma_f32_16x16x32_bf16 v[46:49], v[134:137], v[158:161], v[46:49]
	v_mfma_f32_16x16x32_bf16 v[42:45], v[142:145], v[158:161], v[42:45]
	v_mfma_f32_16x16x32_bf16 v[30:33], v[134:137], v[166:169], v[30:33]
	v_mfma_f32_16x16x32_bf16 v[26:29], v[142:145], v[166:169], v[26:29]
	v_mfma_f32_16x16x32_bf16 v[14:17], v[134:137], v[174:177], v[14:17]
	v_mfma_f32_16x16x32_bf16 v[10:13], v[142:145], v[174:177], v[10:13]
	v_mfma_f32_16x16x32_bf16 v[54:57], v[180:183], v[146:149], v[54:57]
	v_mfma_f32_16x16x32_bf16 v[50:53], v[206:209], v[146:149], v[50:53]
	v_mfma_f32_16x16x32_bf16 v[38:41], v[180:183], v[154:157], v[38:41]
	v_mfma_f32_16x16x32_bf16 v[34:37], v[206:209], v[154:157], v[34:37]
	v_mfma_f32_16x16x32_bf16 v[22:25], v[180:183], v[162:165], v[22:25]
	v_mfma_f32_16x16x32_bf16 v[18:21], v[206:209], v[162:165], v[18:21]
	v_mfma_f32_16x16x32_bf16 v[6:9], v[180:183], v[170:173], v[6:9]
	v_mfma_f32_16x16x32_bf16 v[2:5], v[206:209], v[170:173], v[2:5]
	v_mfma_f32_16x16x32_bf16 v[54:57], v[202:205], v[150:153], v[54:57]
	v_mfma_f32_16x16x32_bf16 v[50:53], v[210:213], v[150:153], v[50:53]
	v_mfma_f32_16x16x32_bf16 v[38:41], v[202:205], v[158:161], v[38:41]
	v_mfma_f32_16x16x32_bf16 v[34:37], v[210:213], v[158:161], v[34:37]
	v_mfma_f32_16x16x32_bf16 v[22:25], v[202:205], v[166:169], v[22:25]
	v_mfma_f32_16x16x32_bf16 v[18:21], v[210:213], v[166:169], v[18:21]
	v_mfma_f32_16x16x32_bf16 v[6:9], v[202:205], v[174:177], v[6:9]
	v_mfma_f32_16x16x32_bf16 v[2:5], v[210:213], v[174:177], v[2:5]
	s_setprio 0
	s_barrier
	v_or_b32_e32 v122, 0x18000, v200
	v_add_u32_e32 v134, 0x18400, v200
	v_add_u32_e32 v138, 0x18800, v200
	v_add_u32_e32 v142, 0x18c00, v200
	ds_read_b128 v[122:125], v122
	ds_read_b128 v[134:137], v134
	ds_read_b128 v[138:141], v138
	ds_read_b128 v[142:145], v142
	s_lshl_b32 s5, s5, 12
	s_lshl_b32 s6, s6, 7
	s_add_i32 s5, s6, s5
	s_add_i32 s5, s5, 0x80000
	v_readfirstlane_b32 s6, v191
	v_add_u32_e32 v180, s5, v184
	s_mov_b32 m0, s6
	ds_read_b128 v[146:149], v199 offset:32768
	ds_read_b128 v[150:153], v199 offset:33792
	ds_read_b128 v[154:157], v199 offset:34816
	ds_read_b128 v[158:161], v199 offset:35840
	ds_read_b128 v[162:165], v199 offset:36864
	ds_read_b128 v[166:169], v199 offset:37888
	ds_read_b128 v[170:173], v199 offset:38912
	ds_read_b128 v[174:177], v199 offset:39936
	global_load_lds_dwordx4 v180, s[80:81]
	v_add_u32_e32 v180, s5, v185
	s_bitset1_b32 m0, 13
	s_nop 0
	global_load_lds_dwordx4 v180, s[80:81]
	s_waitcnt lgkmcnt(8)
	v_or_b32_e32 v180, 0x1c000, v200
	v_add_u32_e32 v202, 0x1c400, v200
	v_add_u32_e32 v206, 0x1c800, v200
	v_add_u32_e32 v210, 0x1cc00, v200
	ds_read_b128 v[180:183], v180
	ds_read_b128 v[202:205], v202
	ds_read_b128 v[206:209], v206
	ds_read_b128 v[210:213], v210
	s_waitcnt vmcnt(8)
	s_waitcnt lgkmcnt(0)
	s_barrier
	s_setprio 1
	v_mfma_f32_16x16x32_bf16 v[130:133], v[122:125], v[146:149], v[130:133]
	v_mfma_f32_16x16x32_bf16 v[126:129], v[138:141], v[146:149], v[126:129]
	v_mfma_f32_16x16x32_bf16 v[110:113], v[122:125], v[154:157], v[110:113]
	v_mfma_f32_16x16x32_bf16 v[106:109], v[138:141], v[154:157], v[106:109]
	v_mfma_f32_16x16x32_bf16 v[94:97], v[122:125], v[162:165], v[94:97]
	v_mfma_f32_16x16x32_bf16 v[90:93], v[138:141], v[162:165], v[90:93]
	v_mfma_f32_16x16x32_bf16 v[78:81], v[122:125], v[170:173], v[78:81]
	v_mfma_f32_16x16x32_bf16 v[74:77], v[138:141], v[170:173], v[74:77]
	v_mfma_f32_16x16x32_bf16 v[130:133], v[134:137], v[150:153], v[130:133]
	v_mfma_f32_16x16x32_bf16 v[126:129], v[142:145], v[150:153], v[126:129]
	v_mfma_f32_16x16x32_bf16 v[110:113], v[134:137], v[158:161], v[110:113]
	v_mfma_f32_16x16x32_bf16 v[106:109], v[142:145], v[158:161], v[106:109]
	v_mfma_f32_16x16x32_bf16 v[94:97], v[134:137], v[166:169], v[94:97]
	v_mfma_f32_16x16x32_bf16 v[90:93], v[142:145], v[166:169], v[90:93]
	v_mfma_f32_16x16x32_bf16 v[78:81], v[134:137], v[174:177], v[78:81]
	v_mfma_f32_16x16x32_bf16 v[74:77], v[142:145], v[174:177], v[74:77]
	v_mfma_f32_16x16x32_bf16 v[118:121], v[180:183], v[146:149], v[118:121]
	v_mfma_f32_16x16x32_bf16 v[114:117], v[206:209], v[146:149], v[114:117]
	v_mfma_f32_16x16x32_bf16 v[102:105], v[180:183], v[154:157], v[102:105]
	v_mfma_f32_16x16x32_bf16 v[98:101], v[206:209], v[154:157], v[98:101]
	v_mfma_f32_16x16x32_bf16 v[86:89], v[180:183], v[162:165], v[86:89]
	v_mfma_f32_16x16x32_bf16 v[82:85], v[206:209], v[162:165], v[82:85]
	v_mfma_f32_16x16x32_bf16 v[70:73], v[180:183], v[170:173], v[70:73]
	v_mfma_f32_16x16x32_bf16 v[66:69], v[206:209], v[170:173], v[66:69]
	v_mfma_f32_16x16x32_bf16 v[118:121], v[202:205], v[150:153], v[118:121]
	v_mfma_f32_16x16x32_bf16 v[114:117], v[210:213], v[150:153], v[114:117]
	v_mfma_f32_16x16x32_bf16 v[102:105], v[202:205], v[158:161], v[102:105]
	v_mfma_f32_16x16x32_bf16 v[98:101], v[210:213], v[158:161], v[98:101]
	v_mfma_f32_16x16x32_bf16 v[86:89], v[202:205], v[166:169], v[86:89]
	v_mfma_f32_16x16x32_bf16 v[82:85], v[210:213], v[166:169], v[82:85]
	v_mfma_f32_16x16x32_bf16 v[70:73], v[202:205], v[174:177], v[70:73]
	v_mfma_f32_16x16x32_bf16 v[66:69], v[210:213], v[174:177], v[66:69]
	s_setprio 0
	s_barrier
	s_or_b32 s5, s7, 64
	s_or_b32 s3, s5, s3
	s_lshl_b32 s3, s3, 1
	v_readfirstlane_b32 s6, v193
	v_add_u32_e32 v214, s3, v184
	s_mov_b32 m0, s6
	global_load_lds_dwordx4 v214, s[74:75]
	v_add_u32_e32 v214, s3, v185
	s_bitset1_b32 m0, 13
	s_nop 0
	global_load_lds_dwordx4 v214, s[74:75]
	s_or_b32 s3, s5, s10
	s_lshl_b32 s3, s3, 1
	v_readfirstlane_b32 s6, v195
	v_add_u32_e32 v214, s3, v184
	s_mov_b32 m0, s6
	ds_read_b128 v[146:149], v199 offset:49152
	ds_read_b128 v[150:153], v199 offset:50176
	ds_read_b128 v[154:157], v199 offset:51200
	ds_read_b128 v[158:161], v199 offset:52224
	ds_read_b128 v[162:165], v199 offset:53248
	ds_read_b128 v[166:169], v199 offset:54272
	ds_read_b128 v[170:173], v199 offset:55296
	ds_read_b128 v[174:177], v199 offset:56320
	global_load_lds_dwordx4 v214, s[80:81]
	v_add_u32_e32 v214, s3, v185
	s_bitset1_b32 m0, 13
	s_nop 0
	global_load_lds_dwordx4 v214, s[80:81]
	s_or_b32 s3, s11, s5
	s_lshl_b32 s3, s3, 1
	v_readfirstlane_b32 s5, v197
	v_add_u32_e32 v215, s3, v184
	s_mov_b32 m0, s5
	s_nop 0
	global_load_lds_dwordx4 v215, s[74:75]
	v_add_u32_e32 v215, s3, v185
	s_bitset1_b32 m0, 13
	s_nop 0
	global_load_lds_dwordx4 v215, s[74:75]
	s_waitcnt vmcnt(8)
	s_waitcnt lgkmcnt(0)
	s_barrier
	s_setprio 1
	v_mfma_f32_16x16x32_bf16 v[62:65], v[122:125], v[146:149], v[62:65]
	v_mfma_f32_16x16x32_bf16 v[58:61], v[138:141], v[146:149], v[58:61]
	v_mfma_f32_16x16x32_bf16 v[46:49], v[122:125], v[154:157], v[46:49]
	v_mfma_f32_16x16x32_bf16 v[42:45], v[138:141], v[154:157], v[42:45]
	v_mfma_f32_16x16x32_bf16 v[30:33], v[122:125], v[162:165], v[30:33]
	v_mfma_f32_16x16x32_bf16 v[26:29], v[138:141], v[162:165], v[26:29]
	v_mfma_f32_16x16x32_bf16 v[14:17], v[122:125], v[170:173], v[14:17]
	v_mfma_f32_16x16x32_bf16 v[10:13], v[138:141], v[170:173], v[10:13]
	v_mfma_f32_16x16x32_bf16 v[62:65], v[134:137], v[150:153], v[62:65]
	v_mfma_f32_16x16x32_bf16 v[58:61], v[142:145], v[150:153], v[58:61]
	v_mfma_f32_16x16x32_bf16 v[46:49], v[134:137], v[158:161], v[46:49]
	v_mfma_f32_16x16x32_bf16 v[42:45], v[142:145], v[158:161], v[42:45]
	v_mfma_f32_16x16x32_bf16 v[30:33], v[134:137], v[166:169], v[30:33]
	v_mfma_f32_16x16x32_bf16 v[26:29], v[142:145], v[166:169], v[26:29]
	v_mfma_f32_16x16x32_bf16 v[14:17], v[134:137], v[174:177], v[14:17]
	v_mfma_f32_16x16x32_bf16 v[10:13], v[142:145], v[174:177], v[10:13]
	v_mfma_f32_16x16x32_bf16 v[54:57], v[180:183], v[146:149], v[54:57]
	v_mfma_f32_16x16x32_bf16 v[50:53], v[206:209], v[146:149], v[50:53]
	v_mfma_f32_16x16x32_bf16 v[38:41], v[180:183], v[154:157], v[38:41]
	v_mfma_f32_16x16x32_bf16 v[34:37], v[206:209], v[154:157], v[34:37]
	v_mfma_f32_16x16x32_bf16 v[22:25], v[180:183], v[162:165], v[22:25]
	v_mfma_f32_16x16x32_bf16 v[18:21], v[206:209], v[162:165], v[18:21]
	v_mfma_f32_16x16x32_bf16 v[6:9], v[180:183], v[170:173], v[6:9]
	v_mfma_f32_16x16x32_bf16 v[2:5], v[206:209], v[170:173], v[2:5]
	v_mfma_f32_16x16x32_bf16 v[54:57], v[202:205], v[150:153], v[54:57]
	v_mfma_f32_16x16x32_bf16 v[50:53], v[210:213], v[150:153], v[50:53]
	v_mfma_f32_16x16x32_bf16 v[38:41], v[202:205], v[158:161], v[38:41]
	v_mfma_f32_16x16x32_bf16 v[34:37], v[210:213], v[158:161], v[34:37]
	v_mfma_f32_16x16x32_bf16 v[22:25], v[202:205], v[166:169], v[22:25]
	v_mfma_f32_16x16x32_bf16 v[18:21], v[210:213], v[166:169], v[18:21]
	v_mfma_f32_16x16x32_bf16 v[6:9], v[202:205], v[174:177], v[6:9]
	v_mfma_f32_16x16x32_bf16 v[2:5], v[210:213], v[174:177], v[2:5]
	s_setprio 0
	s_add_i32 s0, s0, 2
	s_cmp_gt_u32 s1, 29
	v_add_u32_e32 v0, 0x100, v0
	s_barrier
	s_cbranch_scc0 .LBB0_414
